# GEMM loops: priority stays raised across both MFMA clusters of a phase (the s_setprio 0 / s_setprio 1 pair between them removed)
# baseline (speedup 1.0000x reference)
.LBB0_193:
	s_add_u32 s8, s66, 0xfffc0080
	s_addc_u32 s9, s67, -1
	s_add_i32 s56, 0, 0x10000
	s_cmp_eq_u32 s91, 12
	s_cselect_b32 s75, s31, s9
	s_cselect_b32 s74, s87, s8
	v_add_u32_e32 v148, s56, v151
	s_cselect_b32 s73, s21, s90
	s_cselect_b32 s72, s88, s89
	s_add_i32 s57, 0, 0x14000
	ds_read_b128 v[140:143], v148
	ds_read_b128 v[144:147], v148 offset:1024
	ds_read_b128 v[154:157], v148 offset:2048
	ds_read_b128 v[158:161], v148 offset:3072
	v_add_u32_e32 v148, s57, v151
	ds_read_b128 v[162:165], v148
	ds_read_b128 v[166:169], v148 offset:1024
	ds_read_b128 v[170:173], v148 offset:2048
	ds_read_b128 v[174:177], v148 offset:3072
	v_lshl_add_u64 v[148:149], s[66:67], 0, v[136:137]
	s_add_i32 m0, s28, 0xc000
	ds_read_b128 v[182:185], v153
	ds_read_b128 v[186:189], v153 offset:1024
	ds_read_b128 v[190:193], v153 offset:2048
	ds_read_b128 v[194:197], v153 offset:3072
	ds_read_b128 v[198:201], v153 offset:4096
	ds_read_b128 v[202:205], v153 offset:5120
	ds_read_b128 v[206:209], v153 offset:6144
	ds_read_b128 v[210:213], v153 offset:7168
	global_load_lds_dwordx4 v[148:149], off
	v_lshl_add_u64 v[148:149], s[66:67], 0, v[138:139]
	s_add_i32 m0, s28, 0xe000
	s_nop 0
	global_load_lds_dwordx4 v[148:149], off
	s_waitcnt vmcnt(8)
	s_waitcnt lgkmcnt(0)
	s_barrier
	s_setprio 1
	s_waitcnt lgkmcnt(0)
	v_mfma_f32_16x16x32_bf16 v[126:129], v[140:143], v[182:185], v[126:129]
	v_mfma_f32_16x16x32_bf16 v[122:125], v[154:157], v[182:185], v[122:125]
	v_mfma_f32_16x16x32_bf16 v[110:113], v[140:143], v[190:193], v[110:113]
	v_mfma_f32_16x16x32_bf16 v[106:109], v[154:157], v[190:193], v[106:109]
	v_mfma_f32_16x16x32_bf16 v[94:97], v[140:143], v[198:201], v[94:97]
	v_mfma_f32_16x16x32_bf16 v[90:93], v[154:157], v[198:201], v[90:93]
	v_mfma_f32_16x16x32_bf16 v[78:81], v[140:143], v[206:209], v[78:81]
	v_mfma_f32_16x16x32_bf16 v[74:77], v[154:157], v[206:209], v[74:77]
	v_mfma_f32_16x16x32_bf16 v[126:129], v[144:147], v[186:189], v[126:129]
	v_mfma_f32_16x16x32_bf16 v[122:125], v[158:161], v[186:189], v[122:125]
	v_mfma_f32_16x16x32_bf16 v[110:113], v[144:147], v[194:197], v[110:113]
	v_mfma_f32_16x16x32_bf16 v[106:109], v[158:161], v[194:197], v[106:109]
	v_mfma_f32_16x16x32_bf16 v[94:97], v[144:147], v[202:205], v[94:97]
	v_mfma_f32_16x16x32_bf16 v[90:93], v[158:161], v[202:205], v[90:93]
	v_mfma_f32_16x16x32_bf16 v[78:81], v[144:147], v[210:213], v[78:81]
	v_mfma_f32_16x16x32_bf16 v[74:77], v[158:161], v[210:213], v[74:77]
	v_mfma_f32_16x16x32_bf16 v[118:121], v[162:165], v[182:185], v[118:121]
	v_mfma_f32_16x16x32_bf16 v[114:117], v[170:173], v[182:185], v[114:117]
	v_mfma_f32_16x16x32_bf16 v[102:105], v[162:165], v[190:193], v[102:105]
	v_mfma_f32_16x16x32_bf16 v[98:101], v[170:173], v[190:193], v[98:101]
	v_mfma_f32_16x16x32_bf16 v[86:89], v[162:165], v[198:201], v[86:89]
	v_mfma_f32_16x16x32_bf16 v[82:85], v[170:173], v[198:201], v[82:85]
	v_mfma_f32_16x16x32_bf16 v[70:73], v[162:165], v[206:209], v[70:73]
	v_mfma_f32_16x16x32_bf16 v[66:69], v[170:173], v[206:209], v[66:69]
	v_mfma_f32_16x16x32_bf16 v[118:121], v[166:169], v[186:189], v[118:121]
	v_mfma_f32_16x16x32_bf16 v[114:117], v[174:177], v[186:189], v[114:117]
	v_mfma_f32_16x16x32_bf16 v[102:105], v[166:169], v[194:197], v[102:105]
	v_mfma_f32_16x16x32_bf16 v[98:101], v[174:177], v[194:197], v[98:101]
	v_mfma_f32_16x16x32_bf16 v[86:89], v[166:169], v[202:205], v[86:89]
	v_mfma_f32_16x16x32_bf16 v[82:85], v[174:177], v[202:205], v[82:85]
	v_mfma_f32_16x16x32_bf16 v[70:73], v[166:169], v[210:213], v[70:73]
	v_mfma_f32_16x16x32_bf16 v[66:69], v[174:177], v[210:213], v[66:69]
	s_setprio 0
	s_barrier
	s_add_i32 s8, s56, s2
	v_lshl_add_u64 v[148:149], s[72:73], 0, v[32:33]
	s_mov_b32 m0, s8
	ds_read_b128 v[182:185], v153 offset:16384
	ds_read_b128 v[186:189], v153 offset:17408
	ds_read_b128 v[190:193], v153 offset:18432
	ds_read_b128 v[194:197], v153 offset:19456
	ds_read_b128 v[198:201], v153 offset:20480
	ds_read_b128 v[202:205], v153 offset:21504
	ds_read_b128 v[206:209], v153 offset:22528
	ds_read_b128 v[210:213], v153 offset:23552
	global_load_lds_dwordx4 v[148:149], off
	s_add_i32 m0, s8, 0x2000
	s_add_u32 s8, s72, 0x40000
	v_lshl_add_u64 v[178:179], s[72:73], 0, v[134:135]
	s_addc_u32 s9, s73, 0
	s_add_i32 s56, s57, s2
	global_load_lds_dwordx4 v[178:179], off
	v_lshl_add_u64 v[214:215], s[8:9], 0, v[32:33]
	s_mov_b32 m0, s56
	v_lshl_add_u64 v[216:217], s[74:75], 0, v[132:133]
	global_load_lds_dwordx4 v[214:215], off
	v_lshl_add_u64 v[214:215], s[8:9], 0, v[134:135]
	s_add_i32 m0, s56, 0x2000
	s_nop 0
	global_load_lds_dwordx4 v[214:215], off
	v_lshl_add_u64 v[214:215], s[74:75], 0, v[130:131]
	s_mov_b32 m0, s28
	s_nop 0
	global_load_lds_dwordx4 v[214:215], off
	s_mov_b32 m0, s76
	s_nop 0
	global_load_lds_dwordx4 v[216:217], off
	s_waitcnt vmcnt(8)
	s_waitcnt lgkmcnt(0)
	s_barrier
	s_setprio 1
	s_waitcnt lgkmcnt(0)
	v_mfma_f32_16x16x32_bf16 v[62:65], v[140:143], v[182:185], v[62:65]
	v_mfma_f32_16x16x32_bf16 v[58:61], v[154:157], v[182:185], v[58:61]
	v_mfma_f32_16x16x32_bf16 v[46:49], v[140:143], v[190:193], v[46:49]
	v_mfma_f32_16x16x32_bf16 v[42:45], v[154:157], v[190:193], v[42:45]
	v_mfma_f32_16x16x32_bf16 v[28:31], v[140:143], v[198:201], v[28:31]
	v_mfma_f32_16x16x32_bf16 v[24:27], v[154:157], v[198:201], v[24:27]
	v_mfma_f32_16x16x32_bf16 v[12:15], v[140:143], v[206:209], v[12:15]
	v_mfma_f32_16x16x32_bf16 v[8:11], v[154:157], v[206:209], v[8:11]
	v_mfma_f32_16x16x32_bf16 v[62:65], v[144:147], v[186:189], v[62:65]
	v_mfma_f32_16x16x32_bf16 v[58:61], v[158:161], v[186:189], v[58:61]
	v_mfma_f32_16x16x32_bf16 v[46:49], v[144:147], v[194:197], v[46:49]
	v_mfma_f32_16x16x32_bf16 v[42:45], v[158:161], v[194:197], v[42:45]
	v_mfma_f32_16x16x32_bf16 v[28:31], v[144:147], v[202:205], v[28:31]
	v_mfma_f32_16x16x32_bf16 v[24:27], v[158:161], v[202:205], v[24:27]
	v_mfma_f32_16x16x32_bf16 v[12:15], v[144:147], v[210:213], v[12:15]
	v_mfma_f32_16x16x32_bf16 v[8:11], v[158:161], v[210:213], v[8:11]
	v_mfma_f32_16x16x32_bf16 v[54:57], v[162:165], v[182:185], v[54:57]
	v_mfma_f32_16x16x32_bf16 v[50:53], v[170:173], v[182:185], v[50:53]
	v_mfma_f32_16x16x32_bf16 v[38:41], v[162:165], v[190:193], v[38:41]
	v_mfma_f32_16x16x32_bf16 v[34:37], v[170:173], v[190:193], v[34:37]
	v_mfma_f32_16x16x32_bf16 v[20:23], v[162:165], v[198:201], v[20:23]
	v_mfma_f32_16x16x32_bf16 v[16:19], v[170:173], v[198:201], v[16:19]
	v_mfma_f32_16x16x32_bf16 v[4:7], v[162:165], v[206:209], v[4:7]
	v_mfma_f32_16x16x32_bf16 v[0:3], v[170:173], v[206:209], v[0:3]
	v_mfma_f32_16x16x32_bf16 v[54:57], v[166:169], v[186:189], v[54:57]
	v_mfma_f32_16x16x32_bf16 v[50:53], v[174:177], v[186:189], v[50:53]
	v_mfma_f32_16x16x32_bf16 v[38:41], v[166:169], v[194:197], v[38:41]
	v_mfma_f32_16x16x32_bf16 v[34:37], v[174:177], v[194:197], v[34:37]
	v_mfma_f32_16x16x32_bf16 v[20:23], v[166:169], v[202:205], v[20:23]
	v_mfma_f32_16x16x32_bf16 v[16:19], v[174:177], v[202:205], v[16:19]
	v_mfma_f32_16x16x32_bf16 v[4:7], v[166:169], v[210:213], v[4:7]
	v_mfma_f32_16x16x32_bf16 v[0:3], v[174:177], v[210:213], v[0:3]
	s_setprio 0
	s_barrier
	s_add_i32 s56, 0, 0x18000
	s_add_i32 s57, 0, 0x1c000
	v_add_u32_e32 v158, s56, v151
	v_add_u32_e32 v174, s57, v151
	ds_read_b128 v[140:143], v158
	ds_read_b128 v[144:147], v158 offset:1024
	ds_read_b128 v[154:157], v158 offset:2048
	ds_read_b128 v[158:161], v158 offset:3072
	ds_read_b128 v[162:165], v174
	ds_read_b128 v[166:169], v174 offset:1024
	ds_read_b128 v[170:173], v174 offset:2048
	ds_read_b128 v[174:177], v174 offset:3072
	s_add_u32 s8, s74, 0x40000
	s_addc_u32 s9, s75, 0
	s_mov_b32 m0, s77
	v_lshl_add_u64 v[228:229], s[8:9], 0, v[130:131]
	ds_read_b128 v[182:185], v153 offset:32768
	ds_read_b128 v[186:189], v153 offset:33792
	ds_read_b128 v[190:193], v153 offset:34816
	ds_read_b128 v[194:197], v153 offset:35840
	ds_read_b128 v[198:201], v153 offset:36864
	ds_read_b128 v[202:205], v153 offset:37888
	ds_read_b128 v[206:209], v153 offset:38912
	ds_read_b128 v[210:213], v153 offset:39936
	global_load_lds_dwordx4 v[228:229], off
	v_lshl_add_u64 v[228:229], s[8:9], 0, v[132:133]
	s_mov_b32 m0, s83
	s_nop 0
	global_load_lds_dwordx4 v[228:229], off
	s_waitcnt vmcnt(8)
	s_waitcnt lgkmcnt(0)
	s_barrier
	s_setprio 1
	s_waitcnt lgkmcnt(0)
	v_mfma_f32_16x16x32_bf16 v[126:129], v[140:143], v[182:185], v[126:129]
	v_mfma_f32_16x16x32_bf16 v[122:125], v[154:157], v[182:185], v[122:125]
	v_mfma_f32_16x16x32_bf16 v[110:113], v[140:143], v[190:193], v[110:113]
	v_mfma_f32_16x16x32_bf16 v[106:109], v[154:157], v[190:193], v[106:109]
	v_mfma_f32_16x16x32_bf16 v[94:97], v[140:143], v[198:201], v[94:97]
	v_mfma_f32_16x16x32_bf16 v[90:93], v[154:157], v[198:201], v[90:93]
	v_mfma_f32_16x16x32_bf16 v[78:81], v[140:143], v[206:209], v[78:81]
	v_mfma_f32_16x16x32_bf16 v[74:77], v[154:157], v[206:209], v[74:77]
	v_mfma_f32_16x16x32_bf16 v[126:129], v[144:147], v[186:189], v[126:129]
	v_mfma_f32_16x16x32_bf16 v[122:125], v[158:161], v[186:189], v[122:125]
	v_mfma_f32_16x16x32_bf16 v[110:113], v[144:147], v[194:197], v[110:113]
	v_mfma_f32_16x16x32_bf16 v[106:109], v[158:161], v[194:197], v[106:109]
	v_mfma_f32_16x16x32_bf16 v[94:97], v[144:147], v[202:205], v[94:97]
	v_mfma_f32_16x16x32_bf16 v[90:93], v[158:161], v[202:205], v[90:93]
	v_mfma_f32_16x16x32_bf16 v[78:81], v[144:147], v[210:213], v[78:81]
	v_mfma_f32_16x16x32_bf16 v[74:77], v[158:161], v[210:213], v[74:77]
	v_mfma_f32_16x16x32_bf16 v[118:121], v[162:165], v[182:185], v[118:121]
	v_mfma_f32_16x16x32_bf16 v[114:117], v[170:173], v[182:185], v[114:117]
	v_mfma_f32_16x16x32_bf16 v[102:105], v[162:165], v[190:193], v[102:105]
	v_mfma_f32_16x16x32_bf16 v[98:101], v[170:173], v[190:193], v[98:101]
	v_mfma_f32_16x16x32_bf16 v[86:89], v[162:165], v[198:201], v[86:89]
	v_mfma_f32_16x16x32_bf16 v[82:85], v[170:173], v[198:201], v[82:85]
	v_mfma_f32_16x16x32_bf16 v[70:73], v[162:165], v[206:209], v[70:73]
	v_mfma_f32_16x16x32_bf16 v[66:69], v[170:173], v[206:209], v[66:69]
	v_mfma_f32_16x16x32_bf16 v[118:121], v[166:169], v[186:189], v[118:121]
	v_mfma_f32_16x16x32_bf16 v[114:117], v[174:177], v[186:189], v[114:117]
	v_mfma_f32_16x16x32_bf16 v[102:105], v[166:169], v[194:197], v[102:105]
	v_mfma_f32_16x16x32_bf16 v[98:101], v[174:177], v[194:197], v[98:101]
	v_mfma_f32_16x16x32_bf16 v[86:89], v[166:169], v[202:205], v[86:89]
	v_mfma_f32_16x16x32_bf16 v[82:85], v[174:177], v[202:205], v[82:85]
	v_mfma_f32_16x16x32_bf16 v[70:73], v[166:169], v[210:213], v[70:73]
	v_mfma_f32_16x16x32_bf16 v[66:69], v[174:177], v[210:213], v[66:69]
	s_setprio 0
	s_barrier
	s_add_i32 s8, s56, s2
	v_lshl_add_u64 v[148:149], v[148:149], 0, s[38:39]
	s_mov_b32 m0, s8
	ds_read_b128 v[182:185], v153 offset:49152
	ds_read_b128 v[186:189], v153 offset:50176
	ds_read_b128 v[190:193], v153 offset:51200
	ds_read_b128 v[194:197], v153 offset:52224
	ds_read_b128 v[198:201], v153 offset:53248
	ds_read_b128 v[202:205], v153 offset:54272
	ds_read_b128 v[206:209], v153 offset:55296
	ds_read_b128 v[210:213], v153 offset:56320
	global_load_lds_dwordx4 v[148:149], off
	s_add_i32 m0, s8, 0x2000
	s_add_u32 s8, s72, 0x40080
	v_lshl_add_u64 v[148:149], v[178:179], 0, s[38:39]
	s_addc_u32 s9, s73, 0
	s_add_i32 s56, s57, s2
	global_load_lds_dwordx4 v[148:149], off
	v_lshl_add_u64 v[148:149], s[8:9], 0, v[32:33]
	s_mov_b32 m0, s56
	s_nop 0
	global_load_lds_dwordx4 v[148:149], off
	v_lshl_add_u64 v[148:149], s[8:9], 0, v[134:135]
	s_add_i32 m0, s56, 0x2000
	s_nop 0
	global_load_lds_dwordx4 v[148:149], off
	v_lshl_add_u64 v[148:149], v[214:215], 0, s[38:39]
	s_mov_b32 m0, s84
	s_nop 0
	global_load_lds_dwordx4 v[148:149], off
	v_lshl_add_u64 v[148:149], v[216:217], 0, s[38:39]
	s_mov_b32 m0, s85
	s_nop 0
	global_load_lds_dwordx4 v[148:149], off
	s_waitcnt vmcnt(8)
	s_waitcnt lgkmcnt(0)
	s_barrier
	s_setprio 1
	s_waitcnt lgkmcnt(0)
	v_mfma_f32_16x16x32_bf16 v[62:65], v[140:143], v[182:185], v[62:65]
	v_mfma_f32_16x16x32_bf16 v[58:61], v[154:157], v[182:185], v[58:61]
	v_mfma_f32_16x16x32_bf16 v[46:49], v[140:143], v[190:193], v[46:49]
	v_mfma_f32_16x16x32_bf16 v[42:45], v[154:157], v[190:193], v[42:45]
	v_mfma_f32_16x16x32_bf16 v[28:31], v[140:143], v[198:201], v[28:31]
	v_mfma_f32_16x16x32_bf16 v[24:27], v[154:157], v[198:201], v[24:27]
	v_mfma_f32_16x16x32_bf16 v[12:15], v[140:143], v[206:209], v[12:15]
	v_mfma_f32_16x16x32_bf16 v[8:11], v[154:157], v[206:209], v[8:11]
	v_mfma_f32_16x16x32_bf16 v[62:65], v[144:147], v[186:189], v[62:65]
	v_mfma_f32_16x16x32_bf16 v[58:61], v[158:161], v[186:189], v[58:61]
	v_mfma_f32_16x16x32_bf16 v[46:49], v[144:147], v[194:197], v[46:49]
	v_mfma_f32_16x16x32_bf16 v[42:45], v[158:161], v[194:197], v[42:45]
	v_mfma_f32_16x16x32_bf16 v[28:31], v[144:147], v[202:205], v[28:31]
	v_mfma_f32_16x16x32_bf16 v[24:27], v[158:161], v[202:205], v[24:27]
	v_mfma_f32_16x16x32_bf16 v[12:15], v[144:147], v[210:213], v[12:15]
	v_mfma_f32_16x16x32_bf16 v[8:11], v[158:161], v[210:213], v[8:11]
	v_mfma_f32_16x16x32_bf16 v[54:57], v[162:165], v[182:185], v[54:57]
	v_mfma_f32_16x16x32_bf16 v[50:53], v[170:173], v[182:185], v[50:53]
	v_mfma_f32_16x16x32_bf16 v[38:41], v[162:165], v[190:193], v[38:41]
	v_mfma_f32_16x16x32_bf16 v[34:37], v[170:173], v[190:193], v[34:37]
	v_mfma_f32_16x16x32_bf16 v[20:23], v[162:165], v[198:201], v[20:23]
	v_mfma_f32_16x16x32_bf16 v[16:19], v[170:173], v[198:201], v[16:19]
	v_mfma_f32_16x16x32_bf16 v[4:7], v[162:165], v[206:209], v[4:7]
	v_mfma_f32_16x16x32_bf16 v[0:3], v[170:173], v[206:209], v[0:3]
	v_mfma_f32_16x16x32_bf16 v[54:57], v[166:169], v[186:189], v[54:57]
	v_mfma_f32_16x16x32_bf16 v[50:53], v[174:177], v[186:189], v[50:53]
	v_mfma_f32_16x16x32_bf16 v[38:41], v[166:169], v[194:197], v[38:41]
	v_mfma_f32_16x16x32_bf16 v[34:37], v[174:177], v[194:197], v[34:37]
	v_mfma_f32_16x16x32_bf16 v[20:23], v[166:169], v[202:205], v[20:23]
	v_mfma_f32_16x16x32_bf16 v[16:19], v[174:177], v[202:205], v[16:19]
	v_mfma_f32_16x16x32_bf16 v[4:7], v[166:169], v[210:213], v[4:7]
	v_mfma_f32_16x16x32_bf16 v[0:3], v[174:177], v[210:213], v[0:3]
	s_setprio 0
	s_barrier
	s_add_i32 s91, s91, 2
	s_add_u32 s66, s66, 0x100
	s_addc_u32 s67, s67, 0
	s_add_u32 s89, s89, 0x100
	s_addc_u32 s90, s90, 0
	s_cmp_gt_u32 s91, 13
	s_cbranch_scc0 .LBB0_193
	v_readlane_b32 s88, v254, 63
	s_and_b64 vcc, exec, s[16:17]
	v_readlane_b32 s89, v255, 0
	s_cbranch_vccz .LBB0_196
	s_barrier

.LBB0_212:
	s_add_u32 s9, s10, 0xfffe0080
	s_addc_u32 s56, s11, -1
	s_add_i32 s8, 0, 0x10000
	s_cmp_eq_u32 s94, 4
	s_cselect_b32 s75, s31, s56
	s_cselect_b32 s74, s90, s9
	s_cselect_b32 s73, s35, s93
	s_cselect_b32 s72, s91, s92
	s_add_i32 s9, 0, 0x14000
	v_add_u32_e32 v0, s8, v208
	v_add_u32_e32 v12, s9, v208
	ds_read_b128 v[16:19], v0
	ds_read_b128 v[20:23], v0 offset:1024
	ds_read_b128 v[24:27], v0 offset:2048
	ds_read_b128 v[28:31], v0 offset:3072
	ds_read_b128 v[0:3], v12
	ds_read_b128 v[4:7], v12 offset:1024
	ds_read_b128 v[8:11], v12 offset:2048
	ds_read_b128 v[12:15], v12 offset:3072
	v_lshl_add_u64 v[194:195], s[10:11], 0, v[168:169]
	s_add_i32 m0, s83, 0xc000
	ds_read_b128 v[172:175], v210
	ds_read_b128 v[176:179], v210 offset:1024
	ds_read_b128 v[228:231], v210 offset:2048
	ds_read_b128 v[232:235], v210 offset:3072
	ds_read_b128 v[236:239], v210 offset:4096
	ds_read_b128 v[240:243], v210 offset:5120
	ds_read_b128 v[186:189], v210 offset:6144
	ds_read_b128 v[190:193], v210 offset:7168
	global_load_lds_dwordx4 v[194:195], off
	v_lshl_add_u64 v[194:195], s[10:11], 0, v[170:171]
	s_add_i32 m0, s83, 0xe000
	s_nop 0
	global_load_lds_dwordx4 v[194:195], off
	s_waitcnt vmcnt(8)
	s_waitcnt lgkmcnt(0)
	s_barrier
	s_setprio 1
	s_waitcnt lgkmcnt(0)
	v_mfma_f32_16x16x128_f8f6f4 v[158:161], v[16:23], v[172:179], v[158:161]
	v_mfma_f32_16x16x128_f8f6f4 v[154:157], v[24:31], v[172:179], v[154:157]
	v_mfma_f32_16x16x128_f8f6f4 v[142:145], v[16:23], v[228:235], v[142:145]
	v_mfma_f32_16x16x128_f8f6f4 v[138:141], v[24:31], v[228:235], v[138:141]
	v_mfma_f32_16x16x128_f8f6f4 v[126:129], v[16:23], v[236:243], v[126:129]
	v_mfma_f32_16x16x128_f8f6f4 v[122:125], v[24:31], v[236:243], v[122:125]
	v_mfma_f32_16x16x128_f8f6f4 v[110:113], v[16:23], v[186:193], v[110:113]
	v_mfma_f32_16x16x128_f8f6f4 v[106:109], v[24:31], v[186:193], v[106:109]
	v_mfma_f32_16x16x128_f8f6f4 v[150:153], v[0:7], v[172:179], v[150:153]
	v_mfma_f32_16x16x128_f8f6f4 v[146:149], v[8:15], v[172:179], v[146:149]
	v_mfma_f32_16x16x128_f8f6f4 v[134:137], v[0:7], v[228:235], v[134:137]
	v_mfma_f32_16x16x128_f8f6f4 v[130:133], v[8:15], v[228:235], v[130:133]
	v_mfma_f32_16x16x128_f8f6f4 v[118:121], v[0:7], v[236:243], v[118:121]
	v_mfma_f32_16x16x128_f8f6f4 v[114:117], v[8:15], v[236:243], v[114:117]
	v_mfma_f32_16x16x128_f8f6f4 v[102:105], v[0:7], v[186:193], v[102:105]
	v_mfma_f32_16x16x128_f8f6f4 v[98:101], v[8:15], v[186:193], v[98:101]
	s_setprio 0
	s_barrier
	s_add_i32 s8, s8, s77
	v_lshl_add_u64 v[172:173], s[72:73], 0, v[32:33]
	s_mov_b32 m0, s8
	ds_read_b128 v[186:189], v210 offset:16384
	ds_read_b128 v[190:193], v210 offset:17408
	ds_read_b128 v[228:231], v210 offset:18432
	ds_read_b128 v[232:235], v210 offset:19456
	ds_read_b128 v[236:239], v210 offset:20480
	ds_read_b128 v[240:243], v210 offset:21504
	ds_read_b128 v[194:197], v210 offset:22528
	ds_read_b128 v[198:201], v210 offset:23552
	global_load_lds_dwordx4 v[172:173], off
	s_add_i32 m0, s8, 0x2000
	s_add_u32 s96, s72, 0x20000
	v_lshl_add_u64 v[174:175], s[72:73], 0, v[166:167]
	s_addc_u32 s97, s73, 0
	s_add_i32 s8, s9, s77
	global_load_lds_dwordx4 v[174:175], off
	v_lshl_add_u64 v[176:177], s[96:97], 0, v[32:33]
	s_mov_b32 m0, s8
	v_lshl_add_u64 v[178:179], s[74:75], 0, v[164:165]
	global_load_lds_dwordx4 v[176:177], off
	v_lshl_add_u64 v[176:177], s[96:97], 0, v[166:167]
	s_add_i32 m0, s8, 0x2000
	s_nop 0
	global_load_lds_dwordx4 v[176:177], off
	v_lshl_add_u64 v[176:177], s[74:75], 0, v[162:163]
	s_mov_b32 m0, s83
	s_nop 0
	global_load_lds_dwordx4 v[176:177], off
	s_mov_b32 m0, s16
	s_nop 0
	global_load_lds_dwordx4 v[178:179], off
	s_waitcnt vmcnt(8)
	s_waitcnt lgkmcnt(0)
	s_barrier
	s_setprio 1
	s_waitcnt lgkmcnt(0)
	v_mfma_f32_16x16x128_f8f6f4 v[94:97], v[16:23], v[186:193], v[94:97]
	v_mfma_f32_16x16x128_f8f6f4 v[90:93], v[24:31], v[186:193], v[90:93]
	v_mfma_f32_16x16x128_f8f6f4 v[78:81], v[16:23], v[228:235], v[78:81]
	v_mfma_f32_16x16x128_f8f6f4 v[74:77], v[24:31], v[228:235], v[74:77]
	v_mfma_f32_16x16x128_f8f6f4 v[62:65], v[16:23], v[236:243], v[62:65]
	v_mfma_f32_16x16x128_f8f6f4 v[58:61], v[24:31], v[236:243], v[58:61]
	v_mfma_f32_16x16x128_f8f6f4 v[46:49], v[16:23], v[194:201], v[46:49]
	v_mfma_f32_16x16x128_f8f6f4 v[42:45], v[24:31], v[194:201], v[42:45]
	v_mfma_f32_16x16x128_f8f6f4 v[86:89], v[0:7], v[186:193], v[86:89]
	v_mfma_f32_16x16x128_f8f6f4 v[82:85], v[8:15], v[186:193], v[82:85]
	v_mfma_f32_16x16x128_f8f6f4 v[70:73], v[0:7], v[228:235], v[70:73]
	v_mfma_f32_16x16x128_f8f6f4 v[66:69], v[8:15], v[228:235], v[66:69]
	v_mfma_f32_16x16x128_f8f6f4 v[54:57], v[0:7], v[236:243], v[54:57]
	v_mfma_f32_16x16x128_f8f6f4 v[50:53], v[8:15], v[236:243], v[50:53]
	v_mfma_f32_16x16x128_f8f6f4 v[38:41], v[0:7], v[194:201], v[38:41]
	v_mfma_f32_16x16x128_f8f6f4 v[34:37], v[8:15], v[194:201], v[34:37]
	s_setprio 0
	s_barrier
	s_add_i32 s56, 0, 0x18000
	s_add_i32 s57, 0, 0x1c000
	v_add_u32_e32 v12, s56, v208
	v_add_u32_e32 v28, s57, v208
	ds_read_b128 v[0:3], v12
	ds_read_b128 v[4:7], v12 offset:1024
	ds_read_b128 v[8:11], v12 offset:2048
	ds_read_b128 v[12:15], v12 offset:3072
	ds_read_b128 v[16:19], v28
	ds_read_b128 v[20:23], v28 offset:1024
	ds_read_b128 v[24:27], v28 offset:2048
	ds_read_b128 v[28:31], v28 offset:3072
	s_add_u32 s8, s74, 0x20000
	s_addc_u32 s9, s75, 0
	s_mov_b32 m0, s17
	v_lshl_add_u64 v[244:245], s[8:9], 0, v[162:163]
	ds_read_b128 v[186:189], v210 offset:32768
	ds_read_b128 v[190:193], v210 offset:33792
	ds_read_b128 v[194:197], v210 offset:34816
	ds_read_b128 v[198:201], v210 offset:35840
	ds_read_b128 v[228:231], v210 offset:36864
	ds_read_b128 v[232:235], v210 offset:37888
	ds_read_b128 v[236:239], v210 offset:38912
	ds_read_b128 v[240:243], v210 offset:39936
	global_load_lds_dwordx4 v[244:245], off
	v_lshl_add_u64 v[244:245], s[8:9], 0, v[164:165]
	s_mov_b32 m0, s84
	s_nop 0
	global_load_lds_dwordx4 v[244:245], off
	s_waitcnt vmcnt(8)
	s_waitcnt lgkmcnt(0)
	s_barrier
	s_setprio 1
	s_waitcnt lgkmcnt(0)
	v_mfma_f32_16x16x128_f8f6f4 v[158:161], v[0:7], v[186:193], v[158:161]
	v_mfma_f32_16x16x128_f8f6f4 v[154:157], v[8:15], v[186:193], v[154:157]
	v_mfma_f32_16x16x128_f8f6f4 v[142:145], v[0:7], v[194:201], v[142:145]
	v_mfma_f32_16x16x128_f8f6f4 v[138:141], v[8:15], v[194:201], v[138:141]
	v_mfma_f32_16x16x128_f8f6f4 v[126:129], v[0:7], v[228:235], v[126:129]
	v_mfma_f32_16x16x128_f8f6f4 v[122:125], v[8:15], v[228:235], v[122:125]
	v_mfma_f32_16x16x128_f8f6f4 v[110:113], v[0:7], v[236:243], v[110:113]
	v_mfma_f32_16x16x128_f8f6f4 v[106:109], v[8:15], v[236:243], v[106:109]
	v_mfma_f32_16x16x128_f8f6f4 v[150:153], v[16:23], v[186:193], v[150:153]
	v_mfma_f32_16x16x128_f8f6f4 v[146:149], v[24:31], v[186:193], v[146:149]
	v_mfma_f32_16x16x128_f8f6f4 v[134:137], v[16:23], v[194:201], v[134:137]
	v_mfma_f32_16x16x128_f8f6f4 v[130:133], v[24:31], v[194:201], v[130:133]
	v_mfma_f32_16x16x128_f8f6f4 v[118:121], v[16:23], v[228:235], v[118:121]
	v_mfma_f32_16x16x128_f8f6f4 v[114:117], v[24:31], v[228:235], v[114:117]
	v_mfma_f32_16x16x128_f8f6f4 v[102:105], v[16:23], v[236:243], v[102:105]
	v_mfma_f32_16x16x128_f8f6f4 v[98:101], v[24:31], v[236:243], v[98:101]
	s_setprio 0
	s_barrier
	s_add_i32 s8, s56, s77
	v_lshl_add_u64 v[172:173], v[172:173], 0, s[38:39]
	s_mov_b32 m0, s8
	ds_read_b128 v[186:189], v210 offset:49152
	ds_read_b128 v[190:193], v210 offset:50176
	ds_read_b128 v[194:197], v210 offset:51200
	ds_read_b128 v[198:201], v210 offset:52224
	ds_read_b128 v[228:231], v210 offset:53248
	ds_read_b128 v[232:235], v210 offset:54272
	ds_read_b128 v[236:239], v210 offset:55296
	ds_read_b128 v[240:243], v210 offset:56320
	global_load_lds_dwordx4 v[172:173], off
	s_add_i32 m0, s8, 0x2000
	s_add_u32 s8, s72, 0x20080
	v_lshl_add_u64 v[172:173], v[174:175], 0, s[38:39]
	s_addc_u32 s9, s73, 0
	s_add_i32 s56, s57, s77
	global_load_lds_dwordx4 v[172:173], off
	v_lshl_add_u64 v[172:173], s[8:9], 0, v[32:33]
	s_mov_b32 m0, s56
	s_nop 0
	global_load_lds_dwordx4 v[172:173], off
	v_lshl_add_u64 v[172:173], s[8:9], 0, v[166:167]
	s_add_i32 m0, s56, 0x2000
	s_nop 0
	global_load_lds_dwordx4 v[172:173], off
	v_lshl_add_u64 v[172:173], v[176:177], 0, s[38:39]
	s_mov_b32 m0, s85
	s_nop 0
	global_load_lds_dwordx4 v[172:173], off
	v_lshl_add_u64 v[172:173], v[178:179], 0, s[38:39]
	s_mov_b32 m0, s86
	s_nop 0
	global_load_lds_dwordx4 v[172:173], off
	s_waitcnt vmcnt(8)
	s_waitcnt lgkmcnt(0)
	s_barrier
	s_setprio 1
	s_waitcnt lgkmcnt(0)
	v_mfma_f32_16x16x128_f8f6f4 v[94:97], v[0:7], v[186:193], v[94:97]
	v_mfma_f32_16x16x128_f8f6f4 v[90:93], v[8:15], v[186:193], v[90:93]
	v_mfma_f32_16x16x128_f8f6f4 v[78:81], v[0:7], v[194:201], v[78:81]
	v_mfma_f32_16x16x128_f8f6f4 v[74:77], v[8:15], v[194:201], v[74:77]
	v_mfma_f32_16x16x128_f8f6f4 v[62:65], v[0:7], v[228:235], v[62:65]
	v_mfma_f32_16x16x128_f8f6f4 v[58:61], v[8:15], v[228:235], v[58:61]
	v_mfma_f32_16x16x128_f8f6f4 v[46:49], v[0:7], v[236:243], v[46:49]
	v_mfma_f32_16x16x128_f8f6f4 v[42:45], v[8:15], v[236:243], v[42:45]
	v_mfma_f32_16x16x128_f8f6f4 v[86:89], v[16:23], v[186:193], v[86:89]
	v_mfma_f32_16x16x128_f8f6f4 v[82:85], v[24:31], v[186:193], v[82:85]
	v_mfma_f32_16x16x128_f8f6f4 v[70:73], v[16:23], v[194:201], v[70:73]
	v_mfma_f32_16x16x128_f8f6f4 v[66:69], v[24:31], v[194:201], v[66:69]
	v_mfma_f32_16x16x128_f8f6f4 v[54:57], v[16:23], v[228:235], v[54:57]
	v_mfma_f32_16x16x128_f8f6f4 v[50:53], v[24:31], v[228:235], v[50:53]
	v_mfma_f32_16x16x128_f8f6f4 v[38:41], v[16:23], v[236:243], v[38:41]
	v_mfma_f32_16x16x128_f8f6f4 v[34:37], v[24:31], v[236:243], v[34:37]
	s_setprio 0
	s_barrier
	s_add_i32 s94, s94, 2
	s_add_u32 s10, s10, 0x100
	s_addc_u32 s11, s11, 0
	s_add_u32 s92, s92, 0x100
	s_addc_u32 s93, s93, 0
	s_cmp_gt_u32 s94, 5
	s_cbranch_scc0 .LBB0_212
	s_and_b64 vcc, exec, s[20:21]
	s_cbranch_vccz .LBB0_215
	s_barrier

.LBB0_485:
	v_readlane_b32 s16, v254, 30
	v_mov_b32_e32 v163, v33
	v_readlane_b32 s17, v254, 31
	v_mov_b32_e32 v165, v33
	s_lshl_b32 s2, s14, 5
	v_lshl_add_u64 v[90:91], s[16:17], 0, v[162:163]
	v_lshl_add_u64 v[92:93], s[16:17], 0, v[164:165]
	s_add_i32 s17, 0, 0x18000
	s_and_b32 s45, s2, 0x60
	s_add_i32 s2, s17, s9
	s_lshl_b32 s16, s44, 13
	v_lshl_add_u64 v[68:69], v[78:79], 0, s[38:39]
	s_mov_b32 m0, s2
	s_add_i32 s73, s2, 0x2000
	s_add_i32 s67, s77, 0x8000
	s_add_i32 s74, s77, 0xa000
	s_waitcnt vmcnt(2)
	s_barrier
	global_load_lds_dwordx4 v[68:69], off
	v_lshl_add_u64 v[70:71], v[80:81], 0, s[38:39]
	s_mov_b32 m0, s73
	s_add_u32 s14, s10, 0x20080
	global_load_lds_dwordx4 v[70:71], off
	v_lshl_add_u64 v[66:67], v[90:91], 0, s[38:39]
	s_mov_b32 m0, s67
	s_addc_u32 s15, s11, 0
	s_add_i32 s18, 0, 0x1c000
	global_load_lds_dwordx4 v[66:67], off
	v_lshl_add_u64 v[72:73], v[92:93], 0, s[38:39]
	s_mov_b32 m0, s74
	s_add_i32 s75, s18, s9
	global_load_lds_dwordx4 v[72:73], off
	v_lshl_add_u64 v[74:75], s[14:15], 0, v[32:33]
	s_mov_b32 m0, s75
	s_add_i32 s76, s75, 0x2000
	global_load_lds_dwordx4 v[74:75], off
	v_lshl_add_u64 v[76:77], s[14:15], 0, v[166:167]
	s_mov_b32 m0, s76
	v_lshlrev_b32_e32 v1, 2, v213
	global_load_lds_dwordx4 v[76:77], off
	v_lshl_or_b32 v0, v213, 6, v214
	v_and_b32_e32 v1, 32, v1
	v_bitop3_b32 v0, v0, s16, v1 bitop3:0xde
	v_lshl_or_b32 v1, s45, 7, v215
	s_add_i32 s85, 0, 0x10000
	v_add_u32_e32 v98, s85, v1
	s_add_i32 s85, s85, s9
	s_add_i32 s87, 0, 0x14000
	s_add_i32 s89, s77, 0xc000
	s_add_i32 s88, s77, 0xe000
	s_add_i32 s84, s85, 0x2000
	s_add_u32 s34, s10, 0x20100
	v_add_u32_e32 v97, s87, v1
	s_addc_u32 s35, s11, 0
	s_add_i32 s87, s87, s9
	s_waitcnt vmcnt(6)
	s_barrier
	s_add_i32 s86, s87, 0x2000
	ds_read_b128 v[4:7], v98
	ds_read_b128 v[8:11], v98 offset:1024
	ds_read_b128 v[16:19], v98 offset:2048
	ds_read_b128 v[20:23], v98 offset:3072
	ds_read_b128 v[100:103], v97
	ds_read_b128 v[104:107], v97 offset:1024
	ds_read_b128 v[108:111], v97 offset:2048
	ds_read_b128 v[112:115], v97 offset:3072
	s_add_u32 s20, s10, 0x20180
	s_addc_u32 s21, s11, 0
	v_add_u32_e32 v95, s18, v1
	s_add_u32 s18, s10, 0x20200
	s_addc_u32 s19, s11, 0
	v_readlane_b32 s14, v254, 16
	s_add_u32 s16, s10, 0x20280
	v_readlane_b32 s15, v254, 17
	v_add_u32_e32 v96, s17, v1
	s_addc_u32 s17, s11, 0
	v_lshl_add_u64 v[86:87], s[14:15], 0, v[162:163]
	v_lshl_add_u64 v[88:89], s[14:15], 0, v[164:165]
	s_add_u32 s14, s10, 0x20300
	s_addc_u32 s15, s11, 0
	s_add_u32 s10, s10, 0x20380
	s_addc_u32 s11, s11, 0
	v_add_u32_e32 v94, 0, v0
	s_cmpk_gt_u32 s8, 0xff
	v_readlane_b32 s8, v254, 18
	v_readlane_b32 s9, v254, 19
	s_mov_b32 m0, s89
	ds_read_b128 v[34:37], v94
	ds_read_b128 v[38:41], v94 offset:1024
	ds_read_b128 v[116:119], v94 offset:2048
	ds_read_b128 v[120:123], v94 offset:3072
	ds_read_b128 v[124:127], v94 offset:4096
	ds_read_b128 v[128:131], v94 offset:5120
	ds_read_b128 v[132:135], v94 offset:6144
	ds_read_b128 v[136:139], v94 offset:7168
	v_lshl_add_u64 v[0:1], s[8:9], 0, v[162:163]
	global_load_lds_dwordx4 v[0:1], off
	v_lshl_add_u64 v[0:1], s[8:9], 0, v[164:165]
	s_mov_b32 m0, s88
	s_nop 0
	global_load_lds_dwordx4 v[0:1], off
	s_waitcnt vmcnt(8)
	s_waitcnt lgkmcnt(0)
	s_barrier
	s_setprio 1
	s_mov_b32 s28, s29
	s_mov_b32 s30, s29
	s_mov_b32 s31, s29
	v_mov_b64_e32 v[64:65], s[30:31]
	v_mov_b64_e32 v[60:61], s[30:31]
	v_mov_b64_e32 v[48:49], s[30:31]
	v_mov_b64_e32 v[44:45], s[30:31]
	v_mov_b64_e32 v[28:29], s[28:29]
	v_mov_b64_e32 v[24:25], s[28:29]
	v_mov_b64_e32 v[12:13], s[28:29]
	v_mov_b64_e32 v[62:63], s[28:29]
	v_mov_b64_e32 v[58:59], s[28:29]
	v_mov_b64_e32 v[46:47], s[28:29]
	v_mov_b64_e32 v[42:43], s[28:29]
	v_mov_b64_e32 v[30:31], s[30:31]
	v_mov_b64_e32 v[26:27], s[30:31]
	v_mov_b64_e32 v[14:15], s[30:31]
	v_mov_b64_e32 v[0:1], s[28:29]
	s_waitcnt lgkmcnt(0)
	v_mfma_f32_16x16x128_f8f6f4 v[62:65], v[4:11], v[34:41], v[62:65]
	v_mfma_f32_16x16x128_f8f6f4 v[58:61], v[16:23], v[34:41], v[58:61]
	v_mfma_f32_16x16x128_f8f6f4 v[46:49], v[4:11], v[116:123], v[46:49]
	v_mfma_f32_16x16x128_f8f6f4 v[42:45], v[16:23], v[116:123], v[42:45]
	v_mfma_f32_16x16x128_f8f6f4 v[28:31], v[4:11], v[124:131], v[28:31]
	v_mfma_f32_16x16x128_f8f6f4 v[24:27], v[16:23], v[124:131], v[24:27]
	v_mfma_f32_16x16x128_f8f6f4 v[12:15], v[4:11], v[132:139], v[12:15]
	v_mov_b64_e32 v[8:9], s[28:29]
	v_mov_b64_e32 v[2:3], s[30:31]
	v_mov_b64_e32 v[10:11], s[30:31]
	v_mfma_f32_16x16x128_f8f6f4 v[8:11], v[16:23], v[132:139], v[8:11]
	v_mov_b64_e32 v[56:57], s[30:31]
	v_mov_b64_e32 v[52:53], s[30:31]
	v_mov_b64_e32 v[54:55], s[28:29]
	v_mov_b64_e32 v[50:51], s[28:29]
	v_mfma_f32_16x16x128_f8f6f4 v[54:57], v[100:107], v[34:41], v[54:57]
	v_mfma_f32_16x16x128_f8f6f4 v[50:53], v[108:115], v[34:41], v[50:53]
	v_mov_b64_e32 v[40:41], s[30:31]
	v_mov_b64_e32 v[36:37], s[30:31]
	v_mov_b64_e32 v[20:21], s[28:29]
	v_mov_b64_e32 v[16:17], s[28:29]
	v_mov_b64_e32 v[4:5], s[28:29]
	v_mov_b64_e32 v[38:39], s[28:29]
	v_mov_b64_e32 v[34:35], s[28:29]
	v_mov_b64_e32 v[22:23], s[30:31]
	v_mov_b64_e32 v[18:19], s[30:31]
	v_mov_b64_e32 v[6:7], s[30:31]
	v_mfma_f32_16x16x128_f8f6f4 v[38:41], v[100:107], v[116:123], v[38:41]
	v_mfma_f32_16x16x128_f8f6f4 v[34:37], v[108:115], v[116:123], v[34:37]
	v_mfma_f32_16x16x128_f8f6f4 v[20:23], v[100:107], v[124:131], v[20:23]
	v_mfma_f32_16x16x128_f8f6f4 v[16:19], v[108:115], v[124:131], v[16:19]
	v_mfma_f32_16x16x128_f8f6f4 v[4:7], v[100:107], v[132:139], v[4:7]
	v_mfma_f32_16x16x128_f8f6f4 v[0:3], v[108:115], v[132:139], v[0:3]
	s_setprio 0
	s_barrier
	s_mov_b64 s[8:9], 0x100
	s_mov_b32 m0, s85
	v_lshl_add_u64 v[100:101], v[78:79], 0, s[8:9]
	global_load_lds_dwordx4 v[100:101], off
	v_lshl_add_u64 v[100:101], v[80:81], 0, s[8:9]
	s_mov_b32 m0, s84
	s_nop 0
	global_load_lds_dwordx4 v[100:101], off
	v_lshl_add_u64 v[100:101], s[34:35], 0, v[32:33]
	s_mov_b32 m0, s87
	s_nop 0
	global_load_lds_dwordx4 v[100:101], off
	v_lshl_add_u64 v[100:101], s[34:35], 0, v[166:167]
	s_mov_b32 m0, s86
	s_nop 0
	global_load_lds_dwordx4 v[100:101], off
	v_lshl_add_u64 v[100:101], v[90:91], 0, s[8:9]
	s_mov_b32 m0, s77
	s_nop 0
	global_load_lds_dwordx4 v[100:101], off
	v_lshl_add_u64 v[100:101], v[92:93], 0, s[8:9]
	s_mov_b32 m0, s83
	s_nop 0
	global_load_lds_dwordx4 v[100:101], off
	s_waitcnt vmcnt(8)
	s_waitcnt lgkmcnt(0)
	s_barrier
	s_barrier
	ds_read_b128 v[100:103], v96
	ds_read_b128 v[104:107], v96 offset:1024
	ds_read_b128 v[108:111], v96 offset:2048
	ds_read_b128 v[112:115], v96 offset:3072
	ds_read_b128 v[116:119], v95
	ds_read_b128 v[120:123], v95 offset:1024
	ds_read_b128 v[124:127], v95 offset:2048
	ds_read_b128 v[128:131], v95 offset:3072
	v_readlane_b32 s8, v254, 20
	v_readlane_b32 s9, v254, 21
	s_mov_b32 m0, s66
	ds_read_b128 v[132:135], v94 offset:32768
	ds_read_b128 v[136:139], v94 offset:33792
	ds_read_b128 v[140:143], v94 offset:34816
	ds_read_b128 v[144:147], v94 offset:35840
	ds_read_b128 v[148:151], v94 offset:36864
	ds_read_b128 v[152:155], v94 offset:37888
	ds_read_b128 v[168:171], v94 offset:38912
	ds_read_b128 v[172:175], v94 offset:39936
	v_lshl_add_u64 v[156:157], s[8:9], 0, v[162:163]
	global_load_lds_dwordx4 v[156:157], off
	v_lshl_add_u64 v[156:157], s[8:9], 0, v[164:165]
	s_mov_b32 m0, s72
	s_nop 0
	global_load_lds_dwordx4 v[156:157], off
	s_waitcnt vmcnt(8)
	s_waitcnt lgkmcnt(0)
	s_barrier
	s_setprio 1
	s_waitcnt lgkmcnt(0)
	v_mfma_f32_16x16x128_f8f6f4 v[62:65], v[100:107], v[132:139], v[62:65]
	v_mfma_f32_16x16x128_f8f6f4 v[58:61], v[108:115], v[132:139], v[58:61]
	v_mfma_f32_16x16x128_f8f6f4 v[46:49], v[100:107], v[140:147], v[46:49]
	v_mfma_f32_16x16x128_f8f6f4 v[42:45], v[108:115], v[140:147], v[42:45]
	v_mfma_f32_16x16x128_f8f6f4 v[28:31], v[100:107], v[148:155], v[28:31]
	v_mfma_f32_16x16x128_f8f6f4 v[24:27], v[108:115], v[148:155], v[24:27]
	v_mfma_f32_16x16x128_f8f6f4 v[12:15], v[100:107], v[168:175], v[12:15]
	v_mfma_f32_16x16x128_f8f6f4 v[8:11], v[108:115], v[168:175], v[8:11]
	v_mfma_f32_16x16x128_f8f6f4 v[54:57], v[116:123], v[132:139], v[54:57]
	v_mfma_f32_16x16x128_f8f6f4 v[50:53], v[124:131], v[132:139], v[50:53]
	v_mfma_f32_16x16x128_f8f6f4 v[38:41], v[116:123], v[140:147], v[38:41]
	v_mfma_f32_16x16x128_f8f6f4 v[34:37], v[124:131], v[140:147], v[34:37]
	v_mfma_f32_16x16x128_f8f6f4 v[20:23], v[116:123], v[148:155], v[20:23]
	v_mfma_f32_16x16x128_f8f6f4 v[16:19], v[124:131], v[148:155], v[16:19]
	v_mfma_f32_16x16x128_f8f6f4 v[4:7], v[116:123], v[168:175], v[4:7]
	v_mfma_f32_16x16x128_f8f6f4 v[0:3], v[124:131], v[168:175], v[0:3]
	s_setprio 0
	s_barrier
	s_mov_b64 s[8:9], 0x180
	s_mov_b32 m0, s2
	v_lshl_add_u64 v[100:101], v[78:79], 0, s[8:9]
	global_load_lds_dwordx4 v[100:101], off
	v_lshl_add_u64 v[100:101], v[80:81], 0, s[8:9]
	s_mov_b32 m0, s73
	s_nop 0
	global_load_lds_dwordx4 v[100:101], off
	v_lshl_add_u64 v[100:101], s[20:21], 0, v[32:33]
	s_mov_b32 m0, s75
	s_nop 0
	global_load_lds_dwordx4 v[100:101], off
	v_lshl_add_u64 v[100:101], s[20:21], 0, v[166:167]
	s_mov_b32 m0, s76
	s_nop 0
	global_load_lds_dwordx4 v[100:101], off
	v_lshl_add_u64 v[100:101], v[90:91], 0, s[8:9]
	s_mov_b32 m0, s67
	s_nop 0
	global_load_lds_dwordx4 v[100:101], off
	v_lshl_add_u64 v[100:101], v[92:93], 0, s[8:9]
	s_mov_b32 m0, s74
	s_nop 0
	global_load_lds_dwordx4 v[100:101], off
	s_waitcnt vmcnt(8)
	s_waitcnt lgkmcnt(0)
	s_barrier
	s_barrier
	ds_read_b128 v[100:103], v98
	ds_read_b128 v[104:107], v98 offset:1024
	ds_read_b128 v[108:111], v98 offset:2048
	ds_read_b128 v[112:115], v98 offset:3072
	ds_read_b128 v[116:119], v97
	ds_read_b128 v[120:123], v97 offset:1024
	ds_read_b128 v[124:127], v97 offset:2048
	ds_read_b128 v[128:131], v97 offset:3072
	v_readlane_b32 s8, v254, 22
	v_readlane_b32 s9, v254, 23
	s_mov_b32 m0, s89
	ds_read_b128 v[132:135], v94
	ds_read_b128 v[136:139], v94 offset:1024
	ds_read_b128 v[140:143], v94 offset:2048
	ds_read_b128 v[144:147], v94 offset:3072
	ds_read_b128 v[148:151], v94 offset:4096
	ds_read_b128 v[152:155], v94 offset:5120
	ds_read_b128 v[168:171], v94 offset:6144
	ds_read_b128 v[172:175], v94 offset:7168
	v_lshl_add_u64 v[156:157], s[8:9], 0, v[162:163]
	global_load_lds_dwordx4 v[156:157], off
	v_lshl_add_u64 v[156:157], s[8:9], 0, v[164:165]
	s_mov_b32 m0, s88
	s_nop 0
	global_load_lds_dwordx4 v[156:157], off
	s_waitcnt vmcnt(8)
	s_waitcnt lgkmcnt(0)
	s_barrier
	s_setprio 1
	s_waitcnt lgkmcnt(0)
	v_mfma_f32_16x16x128_f8f6f4 v[62:65], v[100:107], v[132:139], v[62:65]
	v_mfma_f32_16x16x128_f8f6f4 v[58:61], v[108:115], v[132:139], v[58:61]
	v_mfma_f32_16x16x128_f8f6f4 v[46:49], v[100:107], v[140:147], v[46:49]
	v_mfma_f32_16x16x128_f8f6f4 v[42:45], v[108:115], v[140:147], v[42:45]
	v_mfma_f32_16x16x128_f8f6f4 v[28:31], v[100:107], v[148:155], v[28:31]
	v_mfma_f32_16x16x128_f8f6f4 v[24:27], v[108:115], v[148:155], v[24:27]
	v_mfma_f32_16x16x128_f8f6f4 v[12:15], v[100:107], v[168:175], v[12:15]
	v_mfma_f32_16x16x128_f8f6f4 v[8:11], v[108:115], v[168:175], v[8:11]
	v_mfma_f32_16x16x128_f8f6f4 v[54:57], v[116:123], v[132:139], v[54:57]
	v_mfma_f32_16x16x128_f8f6f4 v[50:53], v[124:131], v[132:139], v[50:53]
	v_mfma_f32_16x16x128_f8f6f4 v[38:41], v[116:123], v[140:147], v[38:41]
	v_mfma_f32_16x16x128_f8f6f4 v[34:37], v[124:131], v[140:147], v[34:37]
	v_mfma_f32_16x16x128_f8f6f4 v[20:23], v[116:123], v[148:155], v[20:23]
	v_mfma_f32_16x16x128_f8f6f4 v[16:19], v[124:131], v[148:155], v[16:19]
	v_mfma_f32_16x16x128_f8f6f4 v[4:7], v[116:123], v[168:175], v[4:7]
	v_mfma_f32_16x16x128_f8f6f4 v[0:3], v[124:131], v[168:175], v[0:3]
	s_setprio 0
	s_barrier
	s_mov_b64 s[8:9], 0x200
	s_mov_b32 m0, s85
	v_lshl_add_u64 v[100:101], v[78:79], 0, s[8:9]
	global_load_lds_dwordx4 v[100:101], off
	v_lshl_add_u64 v[100:101], v[80:81], 0, s[8:9]
	s_mov_b32 m0, s84
	s_nop 0
	global_load_lds_dwordx4 v[100:101], off
	v_lshl_add_u64 v[100:101], s[18:19], 0, v[32:33]
	s_mov_b32 m0, s87
	s_nop 0
	global_load_lds_dwordx4 v[100:101], off
	v_lshl_add_u64 v[100:101], s[18:19], 0, v[166:167]
	s_mov_b32 m0, s86
	s_nop 0
	global_load_lds_dwordx4 v[100:101], off
	v_lshl_add_u64 v[100:101], v[90:91], 0, s[8:9]
	s_mov_b32 m0, s77
	s_nop 0
	global_load_lds_dwordx4 v[100:101], off
	v_lshl_add_u64 v[100:101], v[92:93], 0, s[8:9]
	s_mov_b32 m0, s83
	s_nop 0
	global_load_lds_dwordx4 v[100:101], off
	s_waitcnt vmcnt(8)
	s_waitcnt lgkmcnt(0)
	s_barrier
	s_barrier
	ds_read_b128 v[100:103], v96
	ds_read_b128 v[104:107], v96 offset:1024
	ds_read_b128 v[108:111], v96 offset:2048
	ds_read_b128 v[112:115], v96 offset:3072
	ds_read_b128 v[116:119], v95
	ds_read_b128 v[120:123], v95 offset:1024
	ds_read_b128 v[124:127], v95 offset:2048
	ds_read_b128 v[128:131], v95 offset:3072
	v_readlane_b32 s8, v254, 24
	v_readlane_b32 s9, v254, 25
	s_mov_b32 m0, s66
	ds_read_b128 v[132:135], v94 offset:32768
	ds_read_b128 v[136:139], v94 offset:33792
	ds_read_b128 v[140:143], v94 offset:34816
	ds_read_b128 v[144:147], v94 offset:35840
	ds_read_b128 v[148:151], v94 offset:36864
	ds_read_b128 v[152:155], v94 offset:37888
	ds_read_b128 v[168:171], v94 offset:38912
	ds_read_b128 v[172:175], v94 offset:39936
	v_lshl_add_u64 v[156:157], s[8:9], 0, v[162:163]
	global_load_lds_dwordx4 v[156:157], off
	v_lshl_add_u64 v[156:157], s[8:9], 0, v[164:165]
	s_mov_b32 m0, s72
	s_nop 0
	global_load_lds_dwordx4 v[156:157], off
	s_waitcnt vmcnt(8)
	s_waitcnt lgkmcnt(0)
	s_barrier
	s_setprio 1
	s_waitcnt lgkmcnt(0)
	v_mfma_f32_16x16x128_f8f6f4 v[62:65], v[100:107], v[132:139], v[62:65]
	v_mfma_f32_16x16x128_f8f6f4 v[58:61], v[108:115], v[132:139], v[58:61]
	v_mfma_f32_16x16x128_f8f6f4 v[46:49], v[100:107], v[140:147], v[46:49]
	v_mfma_f32_16x16x128_f8f6f4 v[42:45], v[108:115], v[140:147], v[42:45]
	v_mfma_f32_16x16x128_f8f6f4 v[28:31], v[100:107], v[148:155], v[28:31]
	v_mfma_f32_16x16x128_f8f6f4 v[24:27], v[108:115], v[148:155], v[24:27]
	v_mfma_f32_16x16x128_f8f6f4 v[12:15], v[100:107], v[168:175], v[12:15]
	v_mfma_f32_16x16x128_f8f6f4 v[8:11], v[108:115], v[168:175], v[8:11]
	v_mfma_f32_16x16x128_f8f6f4 v[54:57], v[116:123], v[132:139], v[54:57]
	v_mfma_f32_16x16x128_f8f6f4 v[50:53], v[124:131], v[132:139], v[50:53]
	v_mfma_f32_16x16x128_f8f6f4 v[38:41], v[116:123], v[140:147], v[38:41]
	v_mfma_f32_16x16x128_f8f6f4 v[34:37], v[124:131], v[140:147], v[34:37]
	v_mfma_f32_16x16x128_f8f6f4 v[20:23], v[116:123], v[148:155], v[20:23]
	v_mfma_f32_16x16x128_f8f6f4 v[16:19], v[124:131], v[148:155], v[16:19]
	v_mfma_f32_16x16x128_f8f6f4 v[4:7], v[116:123], v[168:175], v[4:7]
	v_mfma_f32_16x16x128_f8f6f4 v[0:3], v[124:131], v[168:175], v[0:3]
	s_setprio 0
	s_barrier
	s_mov_b64 s[8:9], 0x280
	s_mov_b32 m0, s2
	v_lshl_add_u64 v[100:101], v[78:79], 0, s[8:9]
	global_load_lds_dwordx4 v[100:101], off
	v_lshl_add_u64 v[100:101], v[80:81], 0, s[8:9]
	s_mov_b32 m0, s73
	s_nop 0
	global_load_lds_dwordx4 v[100:101], off
	v_lshl_add_u64 v[100:101], s[16:17], 0, v[32:33]
	s_mov_b32 m0, s75
	s_nop 0
	global_load_lds_dwordx4 v[100:101], off
	v_lshl_add_u64 v[100:101], s[16:17], 0, v[166:167]
	s_mov_b32 m0, s76
	s_nop 0
	global_load_lds_dwordx4 v[100:101], off
	v_lshl_add_u64 v[100:101], v[90:91], 0, s[8:9]
	s_mov_b32 m0, s67
	s_nop 0
	global_load_lds_dwordx4 v[100:101], off
	v_lshl_add_u64 v[100:101], v[92:93], 0, s[8:9]
	s_mov_b32 m0, s74
	s_nop 0
	global_load_lds_dwordx4 v[100:101], off
	s_waitcnt vmcnt(8)
	s_waitcnt lgkmcnt(0)
	s_barrier
	s_barrier
	ds_read_b128 v[100:103], v98
	ds_read_b128 v[104:107], v98 offset:1024
	ds_read_b128 v[108:111], v98 offset:2048
	ds_read_b128 v[112:115], v98 offset:3072
	ds_read_b128 v[116:119], v97
	ds_read_b128 v[120:123], v97 offset:1024
	ds_read_b128 v[124:127], v97 offset:2048
	ds_read_b128 v[128:131], v97 offset:3072
	v_readlane_b32 s8, v254, 26
	v_readlane_b32 s9, v254, 27
	s_mov_b32 m0, s89
	ds_read_b128 v[132:135], v94
	ds_read_b128 v[136:139], v94 offset:1024
	ds_read_b128 v[140:143], v94 offset:2048
	ds_read_b128 v[144:147], v94 offset:3072
	ds_read_b128 v[148:151], v94 offset:4096
	ds_read_b128 v[152:155], v94 offset:5120
	ds_read_b128 v[168:171], v94 offset:6144
	ds_read_b128 v[172:175], v94 offset:7168
	v_lshl_add_u64 v[156:157], s[8:9], 0, v[162:163]
	global_load_lds_dwordx4 v[156:157], off
	v_lshl_add_u64 v[156:157], s[8:9], 0, v[164:165]
	s_mov_b32 m0, s88
	s_nop 0
	global_load_lds_dwordx4 v[156:157], off
	s_waitcnt vmcnt(8)
	s_waitcnt lgkmcnt(0)
	s_barrier
	s_setprio 1
	s_waitcnt lgkmcnt(0)
	v_mfma_f32_16x16x128_f8f6f4 v[62:65], v[100:107], v[132:139], v[62:65]
	v_mfma_f32_16x16x128_f8f6f4 v[58:61], v[108:115], v[132:139], v[58:61]
	v_mfma_f32_16x16x128_f8f6f4 v[46:49], v[100:107], v[140:147], v[46:49]
	v_mfma_f32_16x16x128_f8f6f4 v[42:45], v[108:115], v[140:147], v[42:45]
	v_mfma_f32_16x16x128_f8f6f4 v[28:31], v[100:107], v[148:155], v[28:31]
	v_mfma_f32_16x16x128_f8f6f4 v[24:27], v[108:115], v[148:155], v[24:27]
	v_mfma_f32_16x16x128_f8f6f4 v[12:15], v[100:107], v[168:175], v[12:15]
	v_mfma_f32_16x16x128_f8f6f4 v[8:11], v[108:115], v[168:175], v[8:11]
	v_mfma_f32_16x16x128_f8f6f4 v[54:57], v[116:123], v[132:139], v[54:57]
	v_mfma_f32_16x16x128_f8f6f4 v[50:53], v[124:131], v[132:139], v[50:53]
	v_mfma_f32_16x16x128_f8f6f4 v[38:41], v[116:123], v[140:147], v[38:41]
	v_mfma_f32_16x16x128_f8f6f4 v[34:37], v[124:131], v[140:147], v[34:37]
	v_mfma_f32_16x16x128_f8f6f4 v[20:23], v[116:123], v[148:155], v[20:23]
	v_mfma_f32_16x16x128_f8f6f4 v[16:19], v[124:131], v[148:155], v[16:19]
	v_mfma_f32_16x16x128_f8f6f4 v[4:7], v[116:123], v[168:175], v[4:7]
	v_mfma_f32_16x16x128_f8f6f4 v[0:3], v[124:131], v[168:175], v[0:3]
	s_setprio 0
	s_barrier
	s_mov_b64 s[8:9], 0x300
	s_mov_b32 m0, s85
	v_lshl_add_u64 v[100:101], v[78:79], 0, s[8:9]
	global_load_lds_dwordx4 v[100:101], off
	v_lshl_add_u64 v[100:101], v[80:81], 0, s[8:9]
	s_mov_b32 m0, s84
	s_nop 0
	global_load_lds_dwordx4 v[100:101], off
	v_lshl_add_u64 v[100:101], s[14:15], 0, v[32:33]
	s_mov_b32 m0, s87
	s_nop 0
	global_load_lds_dwordx4 v[100:101], off
	v_lshl_add_u64 v[100:101], s[14:15], 0, v[166:167]
	s_mov_b32 m0, s86
	s_nop 0
	global_load_lds_dwordx4 v[100:101], off
	v_lshl_add_u64 v[100:101], v[90:91], 0, s[8:9]
	s_mov_b32 m0, s77
	s_nop 0
	global_load_lds_dwordx4 v[100:101], off
	v_lshl_add_u64 v[100:101], v[92:93], 0, s[8:9]
	s_mov_b32 m0, s83
	s_nop 0
	global_load_lds_dwordx4 v[100:101], off
	s_waitcnt vmcnt(8)
	s_waitcnt lgkmcnt(0)
	s_barrier
	s_barrier
	ds_read_b128 v[100:103], v96
	ds_read_b128 v[104:107], v96 offset:1024
	ds_read_b128 v[108:111], v96 offset:2048
	ds_read_b128 v[112:115], v96 offset:3072
	ds_read_b128 v[116:119], v95
	ds_read_b128 v[120:123], v95 offset:1024
	ds_read_b128 v[124:127], v95 offset:2048
	ds_read_b128 v[128:131], v95 offset:3072
	v_readlane_b32 s8, v254, 28
	v_readlane_b32 s9, v254, 29
	s_mov_b32 m0, s66
	ds_read_b128 v[132:135], v94 offset:32768
	ds_read_b128 v[136:139], v94 offset:33792
	ds_read_b128 v[140:143], v94 offset:34816
	ds_read_b128 v[144:147], v94 offset:35840
	ds_read_b128 v[148:151], v94 offset:36864
	ds_read_b128 v[152:155], v94 offset:37888
	ds_read_b128 v[168:171], v94 offset:38912
	ds_read_b128 v[172:175], v94 offset:39936
	v_lshl_add_u64 v[156:157], s[8:9], 0, v[162:163]
	global_load_lds_dwordx4 v[156:157], off
	v_lshl_add_u64 v[156:157], s[8:9], 0, v[164:165]
	s_mov_b32 m0, s72
	s_nop 0
	global_load_lds_dwordx4 v[156:157], off
	s_waitcnt vmcnt(8)
	s_waitcnt lgkmcnt(0)
	s_barrier
	s_setprio 1
	s_waitcnt lgkmcnt(0)
	v_mfma_f32_16x16x128_f8f6f4 v[62:65], v[100:107], v[132:139], v[62:65]
	v_mfma_f32_16x16x128_f8f6f4 v[58:61], v[108:115], v[132:139], v[58:61]
	v_mfma_f32_16x16x128_f8f6f4 v[46:49], v[100:107], v[140:147], v[46:49]
	v_mfma_f32_16x16x128_f8f6f4 v[42:45], v[108:115], v[140:147], v[42:45]
	v_mfma_f32_16x16x128_f8f6f4 v[28:31], v[100:107], v[148:155], v[28:31]
	v_mfma_f32_16x16x128_f8f6f4 v[24:27], v[108:115], v[148:155], v[24:27]
	v_mfma_f32_16x16x128_f8f6f4 v[12:15], v[100:107], v[168:175], v[12:15]
	v_mfma_f32_16x16x128_f8f6f4 v[8:11], v[108:115], v[168:175], v[8:11]
	v_mfma_f32_16x16x128_f8f6f4 v[54:57], v[116:123], v[132:139], v[54:57]
	v_mfma_f32_16x16x128_f8f6f4 v[50:53], v[124:131], v[132:139], v[50:53]
	v_mfma_f32_16x16x128_f8f6f4 v[38:41], v[116:123], v[140:147], v[38:41]
	v_mfma_f32_16x16x128_f8f6f4 v[34:37], v[124:131], v[140:147], v[34:37]
	v_mfma_f32_16x16x128_f8f6f4 v[20:23], v[116:123], v[148:155], v[20:23]
	v_mfma_f32_16x16x128_f8f6f4 v[16:19], v[124:131], v[148:155], v[16:19]
	v_mfma_f32_16x16x128_f8f6f4 v[4:7], v[116:123], v[168:175], v[4:7]
	v_mfma_f32_16x16x128_f8f6f4 v[0:3], v[124:131], v[168:175], v[0:3]
	s_setprio 0
	s_barrier
	s_mov_b64 s[8:9], 0x380
	s_mov_b32 m0, s2
	v_lshl_add_u64 v[100:101], v[78:79], 0, s[8:9]
	global_load_lds_dwordx4 v[100:101], off
	v_lshl_add_u64 v[100:101], v[80:81], 0, s[8:9]
	s_mov_b32 m0, s73
	s_nop 0
	global_load_lds_dwordx4 v[100:101], off
	v_lshl_add_u64 v[100:101], s[10:11], 0, v[32:33]
	s_mov_b32 m0, s75
	s_nop 0
	global_load_lds_dwordx4 v[100:101], off
	v_lshl_add_u64 v[100:101], s[10:11], 0, v[166:167]
	s_mov_b32 m0, s76
	s_nop 0
	global_load_lds_dwordx4 v[100:101], off
	v_lshl_add_u64 v[100:101], v[90:91], 0, s[8:9]
	s_mov_b32 m0, s67
	s_nop 0
	global_load_lds_dwordx4 v[100:101], off
	v_lshl_add_u64 v[100:101], v[92:93], 0, s[8:9]
	s_mov_b32 m0, s74
	s_nop 0
	global_load_lds_dwordx4 v[100:101], off
	s_waitcnt vmcnt(8)
	s_waitcnt lgkmcnt(0)
	s_barrier
	s_barrier
	ds_read_b128 v[100:103], v98
	ds_read_b128 v[104:107], v98 offset:1024
	ds_read_b128 v[108:111], v98 offset:2048
	ds_read_b128 v[112:115], v98 offset:3072
	ds_read_b128 v[116:119], v97
	ds_read_b128 v[120:123], v97 offset:1024
	ds_read_b128 v[124:127], v97 offset:2048
	ds_read_b128 v[128:131], v97 offset:3072
	v_readlane_b32 s8, v254, 32
	v_readlane_b32 s9, v254, 33
	s_mov_b32 m0, s89
	ds_read_b128 v[132:135], v94
	ds_read_b128 v[136:139], v94 offset:1024
	ds_read_b128 v[140:143], v94 offset:2048
	ds_read_b128 v[144:147], v94 offset:3072
	ds_read_b128 v[148:151], v94 offset:4096
	ds_read_b128 v[152:155], v94 offset:5120
	ds_read_b128 v[166:169], v94 offset:6144
	ds_read_b128 v[170:173], v94 offset:7168
	v_lshl_add_u64 v[98:99], s[8:9], 0, v[162:163]
	global_load_lds_dwordx4 v[98:99], off
	v_lshl_add_u64 v[98:99], s[8:9], 0, v[164:165]
	s_mov_b32 m0, s88
	s_nop 0
	global_load_lds_dwordx4 v[98:99], off
	s_waitcnt vmcnt(8)
	s_waitcnt lgkmcnt(0)
	s_barrier
	s_setprio 1
	s_waitcnt lgkmcnt(0)
	v_mfma_f32_16x16x128_f8f6f4 v[62:65], v[100:107], v[132:139], v[62:65]
	v_mfma_f32_16x16x128_f8f6f4 v[58:61], v[108:115], v[132:139], v[58:61]
	v_mfma_f32_16x16x128_f8f6f4 v[46:49], v[100:107], v[140:147], v[46:49]
	v_mfma_f32_16x16x128_f8f6f4 v[42:45], v[108:115], v[140:147], v[42:45]
	v_mfma_f32_16x16x128_f8f6f4 v[28:31], v[100:107], v[148:155], v[28:31]
	v_mfma_f32_16x16x128_f8f6f4 v[24:27], v[108:115], v[148:155], v[24:27]
	v_mfma_f32_16x16x128_f8f6f4 v[12:15], v[100:107], v[166:173], v[12:15]
	v_mfma_f32_16x16x128_f8f6f4 v[8:11], v[108:115], v[166:173], v[8:11]
	v_mfma_f32_16x16x128_f8f6f4 v[54:57], v[116:123], v[132:139], v[54:57]
	v_mfma_f32_16x16x128_f8f6f4 v[50:53], v[124:131], v[132:139], v[50:53]
	v_mfma_f32_16x16x128_f8f6f4 v[38:41], v[116:123], v[140:147], v[38:41]
	v_mfma_f32_16x16x128_f8f6f4 v[34:37], v[124:131], v[140:147], v[34:37]
	v_mfma_f32_16x16x128_f8f6f4 v[20:23], v[116:123], v[148:155], v[20:23]
	v_mfma_f32_16x16x128_f8f6f4 v[16:19], v[124:131], v[148:155], v[16:19]
	v_mfma_f32_16x16x128_f8f6f4 v[4:7], v[116:123], v[166:173], v[4:7]
	v_mfma_f32_16x16x128_f8f6f4 v[0:3], v[124:131], v[166:173], v[0:3]
	s_setprio 0
	s_barrier
	s_mov_b32 m0, s85
	s_nop 0
	global_load_lds_dwordx4 v[78:79], off
	s_mov_b32 m0, s84
	s_nop 0
	global_load_lds_dwordx4 v[80:81], off
	s_mov_b32 m0, s87
	s_nop 0
	global_load_lds_dwordx4 v[82:83], off
	s_mov_b32 m0, s86
	s_nop 0
	global_load_lds_dwordx4 v[84:85], off
	s_mov_b32 m0, s77
	s_nop 0
	global_load_lds_dwordx4 v[90:91], off
	s_mov_b32 m0, s83
	s_nop 0
	global_load_lds_dwordx4 v[92:93], off
	s_waitcnt vmcnt(8)
	s_waitcnt lgkmcnt(0)
	s_barrier
	s_barrier
	ds_read_b128 v[78:81], v96
	ds_read_b128 v[82:85], v96 offset:1024
	ds_read_b128 v[98:101], v96 offset:2048
	ds_read_b128 v[102:105], v96 offset:3072
	ds_read_b128 v[106:109], v95
	ds_read_b128 v[110:113], v95 offset:1024
	ds_read_b128 v[114:117], v95 offset:2048
	ds_read_b128 v[118:121], v95 offset:3072
	s_mov_b32 m0, s66
	ds_read_b128 v[122:125], v94 offset:32768
	ds_read_b128 v[126:129], v94 offset:33792
	ds_read_b128 v[130:133], v94 offset:34816
	ds_read_b128 v[134:137], v94 offset:35840
	ds_read_b128 v[138:141], v94 offset:36864
	ds_read_b128 v[142:145], v94 offset:37888
	ds_read_b128 v[90:93], v94 offset:38912
	ds_read_b128 v[94:97], v94 offset:39936
	global_load_lds_dwordx4 v[86:87], off
	s_mov_b32 m0, s72
	s_nop 0
	global_load_lds_dwordx4 v[88:89], off
	s_waitcnt vmcnt(8)
	s_waitcnt lgkmcnt(0)
	s_barrier
	s_setprio 1
	s_waitcnt lgkmcnt(0)
	v_mfma_f32_16x16x128_f8f6f4 v[62:65], v[78:85], v[122:129], v[62:65]
	v_mfma_f32_16x16x128_f8f6f4 v[58:61], v[98:105], v[122:129], v[58:61]
	v_mfma_f32_16x16x128_f8f6f4 v[46:49], v[78:85], v[130:137], v[46:49]
	v_mfma_f32_16x16x128_f8f6f4 v[42:45], v[98:105], v[130:137], v[42:45]
	v_mfma_f32_16x16x128_f8f6f4 v[28:31], v[78:85], v[138:145], v[28:31]
	v_mfma_f32_16x16x128_f8f6f4 v[24:27], v[98:105], v[138:145], v[24:27]
	v_mfma_f32_16x16x128_f8f6f4 v[12:15], v[78:85], v[90:97], v[12:15]
	v_mfma_f32_16x16x128_f8f6f4 v[8:11], v[98:105], v[90:97], v[8:11]
	v_mfma_f32_16x16x128_f8f6f4 v[54:57], v[106:113], v[122:129], v[54:57]
	v_mfma_f32_16x16x128_f8f6f4 v[50:53], v[114:121], v[122:129], v[50:53]
	v_mfma_f32_16x16x128_f8f6f4 v[38:41], v[106:113], v[130:137], v[38:41]
	v_mfma_f32_16x16x128_f8f6f4 v[34:37], v[114:121], v[130:137], v[34:37]
	v_mfma_f32_16x16x128_f8f6f4 v[20:23], v[106:113], v[138:145], v[20:23]
	v_mfma_f32_16x16x128_f8f6f4 v[16:19], v[114:121], v[138:145], v[16:19]
	v_mfma_f32_16x16x128_f8f6f4 v[4:7], v[106:113], v[90:97], v[4:7]
	v_mfma_f32_16x16x128_f8f6f4 v[0:3], v[114:121], v[90:97], v[0:3]
	s_setprio 0
	s_barrier
	s_mov_b32 m0, s2
	s_nop 0
	global_load_lds_dwordx4 v[68:69], off
	s_mov_b32 m0, s73
	s_nop 0
	global_load_lds_dwordx4 v[70:71], off
	s_mov_b32 m0, s75
	s_nop 0
	global_load_lds_dwordx4 v[74:75], off
	s_mov_b32 m0, s76
	s_nop 0
	global_load_lds_dwordx4 v[76:77], off
	s_mov_b32 m0, s67
	s_nop 0
	global_load_lds_dwordx4 v[66:67], off
	s_mov_b32 m0, s74
	s_nop 0
	global_load_lds_dwordx4 v[72:73], off
	s_waitcnt vmcnt(8)
	s_waitcnt lgkmcnt(0)
	s_barrier
	s_barrier
	s_cbranch_scc1 .LBB0_487
	s_barrier

.LBB0_652:
	s_add_u32 s8, s10, 0xfffc0080
	s_addc_u32 s9, s11, -1
	s_add_i32 s56, 0, 0x10000
	s_cmp_eq_u32 s93, 12
	s_cselect_b32 s73, s19, s9
	s_cselect_b32 s72, s89, s8
	s_cselect_b32 s67, s21, s92
	s_cselect_b32 s66, s90, s91
	s_add_i32 s57, 0, 0x14000
	v_add_u32_e32 v152, s56, v159
	v_add_u32_e32 v156, s57, v159
	ds_read_b128 v[130:133], v152
	ds_read_b128 v[134:137], v152 offset:1024
	ds_read_b128 v[148:151], v152 offset:2048
	ds_read_b128 v[152:155], v152 offset:3072
	ds_read_b128 v[162:165], v156
	ds_read_b128 v[166:169], v156 offset:1024
	ds_read_b128 v[170:173], v156 offset:2048
	ds_read_b128 v[174:177], v156 offset:3072
	v_lshl_add_u64 v[156:157], s[10:11], 0, v[144:145]
	s_add_i32 m0, s75, 0xc000
	ds_read_b128 v[178:181], v161
	ds_read_b128 v[182:185], v161 offset:1024
	ds_read_b128 v[186:189], v161 offset:2048
	ds_read_b128 v[190:193], v161 offset:3072
	ds_read_b128 v[194:197], v161 offset:4096
	ds_read_b128 v[198:201], v161 offset:5120
	ds_read_b128 v[202:205], v161 offset:6144
	ds_read_b128 v[206:209], v161 offset:7168
	global_load_lds_dwordx4 v[156:157], off
	v_lshl_add_u64 v[156:157], s[10:11], 0, v[146:147]
	s_add_i32 m0, s75, 0xe000
	s_nop 0
	global_load_lds_dwordx4 v[156:157], off
	s_waitcnt vmcnt(8)
	s_waitcnt lgkmcnt(0)
	s_barrier
	s_setprio 1
	s_waitcnt lgkmcnt(0)
	v_mfma_f32_16x16x32_bf16 v[126:129], v[130:133], v[178:181], v[126:129]
	v_mfma_f32_16x16x32_bf16 v[122:125], v[148:151], v[178:181], v[122:125]
	v_mfma_f32_16x16x32_bf16 v[110:113], v[130:133], v[186:189], v[110:113]
	v_mfma_f32_16x16x32_bf16 v[106:109], v[148:151], v[186:189], v[106:109]
	v_mfma_f32_16x16x32_bf16 v[94:97], v[130:133], v[194:197], v[94:97]
	v_mfma_f32_16x16x32_bf16 v[90:93], v[148:151], v[194:197], v[90:93]
	v_mfma_f32_16x16x32_bf16 v[78:81], v[130:133], v[202:205], v[78:81]
	v_mfma_f32_16x16x32_bf16 v[74:77], v[148:151], v[202:205], v[74:77]
	v_mfma_f32_16x16x32_bf16 v[126:129], v[134:137], v[182:185], v[126:129]
	v_mfma_f32_16x16x32_bf16 v[122:125], v[152:155], v[182:185], v[122:125]
	v_mfma_f32_16x16x32_bf16 v[110:113], v[134:137], v[190:193], v[110:113]
	v_mfma_f32_16x16x32_bf16 v[106:109], v[152:155], v[190:193], v[106:109]
	v_mfma_f32_16x16x32_bf16 v[94:97], v[134:137], v[198:201], v[94:97]
	v_mfma_f32_16x16x32_bf16 v[90:93], v[152:155], v[198:201], v[90:93]
	v_mfma_f32_16x16x32_bf16 v[78:81], v[134:137], v[206:209], v[78:81]
	v_mfma_f32_16x16x32_bf16 v[74:77], v[152:155], v[206:209], v[74:77]
	v_mfma_f32_16x16x32_bf16 v[118:121], v[162:165], v[178:181], v[118:121]
	v_mfma_f32_16x16x32_bf16 v[114:117], v[170:173], v[178:181], v[114:117]
	v_mfma_f32_16x16x32_bf16 v[102:105], v[162:165], v[186:189], v[102:105]
	v_mfma_f32_16x16x32_bf16 v[98:101], v[170:173], v[186:189], v[98:101]
	v_mfma_f32_16x16x32_bf16 v[86:89], v[162:165], v[194:197], v[86:89]
	v_mfma_f32_16x16x32_bf16 v[82:85], v[170:173], v[194:197], v[82:85]
	v_mfma_f32_16x16x32_bf16 v[70:73], v[162:165], v[202:205], v[70:73]
	v_mfma_f32_16x16x32_bf16 v[66:69], v[170:173], v[202:205], v[66:69]
	v_mfma_f32_16x16x32_bf16 v[118:121], v[166:169], v[182:185], v[118:121]
	v_mfma_f32_16x16x32_bf16 v[114:117], v[174:177], v[182:185], v[114:117]
	v_mfma_f32_16x16x32_bf16 v[102:105], v[166:169], v[190:193], v[102:105]
	v_mfma_f32_16x16x32_bf16 v[98:101], v[174:177], v[190:193], v[98:101]
	v_mfma_f32_16x16x32_bf16 v[86:89], v[166:169], v[198:201], v[86:89]
	v_mfma_f32_16x16x32_bf16 v[82:85], v[174:177], v[198:201], v[82:85]
	v_mfma_f32_16x16x32_bf16 v[70:73], v[166:169], v[206:209], v[70:73]
	v_mfma_f32_16x16x32_bf16 v[66:69], v[174:177], v[206:209], v[66:69]
	s_setprio 0
	s_barrier
	s_add_i32 s8, s56, s74
	v_lshl_add_u64 v[156:157], s[66:67], 0, v[32:33]
	s_mov_b32 m0, s8
	ds_read_b128 v[178:181], v161 offset:16384
	ds_read_b128 v[182:185], v161 offset:17408
	ds_read_b128 v[186:189], v161 offset:18432
	ds_read_b128 v[190:193], v161 offset:19456
	ds_read_b128 v[194:197], v161 offset:20480
	ds_read_b128 v[198:201], v161 offset:21504
	ds_read_b128 v[202:205], v161 offset:22528
	ds_read_b128 v[206:209], v161 offset:23552
	global_load_lds_dwordx4 v[156:157], off
	s_add_i32 m0, s8, 0x2000
	s_add_u32 s8, s66, 0x40000
	v_lshl_add_u64 v[210:211], s[66:67], 0, v[138:139]
	s_addc_u32 s9, s67, 0
	s_add_i32 s56, s57, s74
	global_load_lds_dwordx4 v[210:211], off
	v_lshl_add_u64 v[212:213], s[8:9], 0, v[32:33]
	s_mov_b32 m0, s56
	v_lshl_add_u64 v[214:215], s[72:73], 0, v[140:141]
	global_load_lds_dwordx4 v[212:213], off
	v_lshl_add_u64 v[212:213], s[8:9], 0, v[138:139]
	s_add_i32 m0, s56, 0x2000
	s_nop 0
	global_load_lds_dwordx4 v[212:213], off
	v_lshl_add_u64 v[212:213], s[72:73], 0, v[142:143]
	s_mov_b32 m0, s75
	s_nop 0
	global_load_lds_dwordx4 v[212:213], off
	s_mov_b32 m0, s76
	s_nop 0
	global_load_lds_dwordx4 v[214:215], off
	s_waitcnt vmcnt(8)
	s_waitcnt lgkmcnt(0)
	s_barrier
	s_setprio 1
	s_waitcnt lgkmcnt(0)
	v_mfma_f32_16x16x32_bf16 v[62:65], v[130:133], v[178:181], v[62:65]
	v_mfma_f32_16x16x32_bf16 v[58:61], v[148:151], v[178:181], v[58:61]
	v_mfma_f32_16x16x32_bf16 v[46:49], v[130:133], v[186:189], v[46:49]
	v_mfma_f32_16x16x32_bf16 v[42:45], v[148:151], v[186:189], v[42:45]
	v_mfma_f32_16x16x32_bf16 v[28:31], v[130:133], v[194:197], v[28:31]
	v_mfma_f32_16x16x32_bf16 v[24:27], v[148:151], v[194:197], v[24:27]
	v_mfma_f32_16x16x32_bf16 v[12:15], v[130:133], v[202:205], v[12:15]
	v_mfma_f32_16x16x32_bf16 v[8:11], v[148:151], v[202:205], v[8:11]
	v_mfma_f32_16x16x32_bf16 v[62:65], v[134:137], v[182:185], v[62:65]
	v_mfma_f32_16x16x32_bf16 v[58:61], v[152:155], v[182:185], v[58:61]
	v_mfma_f32_16x16x32_bf16 v[46:49], v[134:137], v[190:193], v[46:49]
	v_mfma_f32_16x16x32_bf16 v[42:45], v[152:155], v[190:193], v[42:45]
	v_mfma_f32_16x16x32_bf16 v[28:31], v[134:137], v[198:201], v[28:31]
	v_mfma_f32_16x16x32_bf16 v[24:27], v[152:155], v[198:201], v[24:27]
	v_mfma_f32_16x16x32_bf16 v[12:15], v[134:137], v[206:209], v[12:15]
	v_mfma_f32_16x16x32_bf16 v[8:11], v[152:155], v[206:209], v[8:11]
	v_mfma_f32_16x16x32_bf16 v[54:57], v[162:165], v[178:181], v[54:57]
	v_mfma_f32_16x16x32_bf16 v[50:53], v[170:173], v[178:181], v[50:53]
	v_mfma_f32_16x16x32_bf16 v[38:41], v[162:165], v[186:189], v[38:41]
	v_mfma_f32_16x16x32_bf16 v[34:37], v[170:173], v[186:189], v[34:37]
	v_mfma_f32_16x16x32_bf16 v[20:23], v[162:165], v[194:197], v[20:23]
	v_mfma_f32_16x16x32_bf16 v[16:19], v[170:173], v[194:197], v[16:19]
	v_mfma_f32_16x16x32_bf16 v[4:7], v[162:165], v[202:205], v[4:7]
	v_mfma_f32_16x16x32_bf16 v[0:3], v[170:173], v[202:205], v[0:3]
	v_mfma_f32_16x16x32_bf16 v[54:57], v[166:169], v[182:185], v[54:57]
	v_mfma_f32_16x16x32_bf16 v[50:53], v[174:177], v[182:185], v[50:53]
	v_mfma_f32_16x16x32_bf16 v[38:41], v[166:169], v[190:193], v[38:41]
	v_mfma_f32_16x16x32_bf16 v[34:37], v[174:177], v[190:193], v[34:37]
	v_mfma_f32_16x16x32_bf16 v[20:23], v[166:169], v[198:201], v[20:23]
	v_mfma_f32_16x16x32_bf16 v[16:19], v[174:177], v[198:201], v[16:19]
	v_mfma_f32_16x16x32_bf16 v[4:7], v[166:169], v[206:209], v[4:7]
	v_mfma_f32_16x16x32_bf16 v[0:3], v[174:177], v[206:209], v[0:3]
	s_setprio 0
	s_barrier
	s_add_i32 s56, 0, 0x18000
	s_add_i32 s57, 0, 0x1c000
	v_add_u32_e32 v152, s56, v159
	v_add_u32_e32 v174, s57, v159
	ds_read_b128 v[130:133], v152
	ds_read_b128 v[134:137], v152 offset:1024
	ds_read_b128 v[148:151], v152 offset:2048
	ds_read_b128 v[152:155], v152 offset:3072
	ds_read_b128 v[162:165], v174
	ds_read_b128 v[166:169], v174 offset:1024
	ds_read_b128 v[170:173], v174 offset:2048
	ds_read_b128 v[174:177], v174 offset:3072
	s_add_u32 s8, s72, 0x40000
	s_addc_u32 s9, s73, 0
	s_mov_b32 m0, s77
	v_lshl_add_u64 v[216:217], s[8:9], 0, v[142:143]
	ds_read_b128 v[178:181], v161 offset:32768
	ds_read_b128 v[182:185], v161 offset:33792
	ds_read_b128 v[186:189], v161 offset:34816
	ds_read_b128 v[190:193], v161 offset:35840
	ds_read_b128 v[194:197], v161 offset:36864
	ds_read_b128 v[198:201], v161 offset:37888
	ds_read_b128 v[202:205], v161 offset:38912
	ds_read_b128 v[206:209], v161 offset:39936
	global_load_lds_dwordx4 v[216:217], off
	v_lshl_add_u64 v[216:217], s[8:9], 0, v[140:141]
	s_mov_b32 m0, s83
	s_nop 0
	global_load_lds_dwordx4 v[216:217], off
	s_waitcnt vmcnt(8)
	s_waitcnt lgkmcnt(0)
	s_barrier
	s_setprio 1
	s_waitcnt lgkmcnt(0)
	v_mfma_f32_16x16x32_bf16 v[126:129], v[130:133], v[178:181], v[126:129]
	v_mfma_f32_16x16x32_bf16 v[122:125], v[148:151], v[178:181], v[122:125]
	v_mfma_f32_16x16x32_bf16 v[110:113], v[130:133], v[186:189], v[110:113]
	v_mfma_f32_16x16x32_bf16 v[106:109], v[148:151], v[186:189], v[106:109]
	v_mfma_f32_16x16x32_bf16 v[94:97], v[130:133], v[194:197], v[94:97]
	v_mfma_f32_16x16x32_bf16 v[90:93], v[148:151], v[194:197], v[90:93]
	v_mfma_f32_16x16x32_bf16 v[78:81], v[130:133], v[202:205], v[78:81]
	v_mfma_f32_16x16x32_bf16 v[74:77], v[148:151], v[202:205], v[74:77]
	v_mfma_f32_16x16x32_bf16 v[126:129], v[134:137], v[182:185], v[126:129]
	v_mfma_f32_16x16x32_bf16 v[122:125], v[152:155], v[182:185], v[122:125]
	v_mfma_f32_16x16x32_bf16 v[110:113], v[134:137], v[190:193], v[110:113]
	v_mfma_f32_16x16x32_bf16 v[106:109], v[152:155], v[190:193], v[106:109]
	v_mfma_f32_16x16x32_bf16 v[94:97], v[134:137], v[198:201], v[94:97]
	v_mfma_f32_16x16x32_bf16 v[90:93], v[152:155], v[198:201], v[90:93]
	v_mfma_f32_16x16x32_bf16 v[78:81], v[134:137], v[206:209], v[78:81]
	v_mfma_f32_16x16x32_bf16 v[74:77], v[152:155], v[206:209], v[74:77]
	v_mfma_f32_16x16x32_bf16 v[118:121], v[162:165], v[178:181], v[118:121]
	v_mfma_f32_16x16x32_bf16 v[114:117], v[170:173], v[178:181], v[114:117]
	v_mfma_f32_16x16x32_bf16 v[102:105], v[162:165], v[186:189], v[102:105]
	v_mfma_f32_16x16x32_bf16 v[98:101], v[170:173], v[186:189], v[98:101]
	v_mfma_f32_16x16x32_bf16 v[86:89], v[162:165], v[194:197], v[86:89]
	v_mfma_f32_16x16x32_bf16 v[82:85], v[170:173], v[194:197], v[82:85]
	v_mfma_f32_16x16x32_bf16 v[70:73], v[162:165], v[202:205], v[70:73]
	v_mfma_f32_16x16x32_bf16 v[66:69], v[170:173], v[202:205], v[66:69]
	v_mfma_f32_16x16x32_bf16 v[118:121], v[166:169], v[182:185], v[118:121]
	v_mfma_f32_16x16x32_bf16 v[114:117], v[174:177], v[182:185], v[114:117]
	v_mfma_f32_16x16x32_bf16 v[102:105], v[166:169], v[190:193], v[102:105]
	v_mfma_f32_16x16x32_bf16 v[98:101], v[174:177], v[190:193], v[98:101]
	v_mfma_f32_16x16x32_bf16 v[86:89], v[166:169], v[198:201], v[86:89]
	v_mfma_f32_16x16x32_bf16 v[82:85], v[174:177], v[198:201], v[82:85]
	v_mfma_f32_16x16x32_bf16 v[70:73], v[166:169], v[206:209], v[70:73]
	v_mfma_f32_16x16x32_bf16 v[66:69], v[174:177], v[206:209], v[66:69]
	s_setprio 0
	s_barrier
	s_add_i32 s8, s56, s74
	v_lshl_add_u64 v[156:157], v[156:157], 0, s[38:39]
	s_mov_b32 m0, s8
	ds_read_b128 v[178:181], v161 offset:49152
	ds_read_b128 v[182:185], v161 offset:50176
	ds_read_b128 v[186:189], v161 offset:51200
	ds_read_b128 v[190:193], v161 offset:52224
	ds_read_b128 v[194:197], v161 offset:53248
	ds_read_b128 v[198:201], v161 offset:54272
	ds_read_b128 v[202:205], v161 offset:55296
	ds_read_b128 v[206:209], v161 offset:56320
	global_load_lds_dwordx4 v[156:157], off
	s_add_i32 m0, s8, 0x2000
	s_add_u32 s8, s66, 0x40080
	v_lshl_add_u64 v[156:157], v[210:211], 0, s[38:39]
	s_addc_u32 s9, s67, 0
	s_add_i32 s56, s57, s74
	global_load_lds_dwordx4 v[156:157], off
	v_lshl_add_u64 v[156:157], s[8:9], 0, v[32:33]
	s_mov_b32 m0, s56
	s_nop 0
	global_load_lds_dwordx4 v[156:157], off
	v_lshl_add_u64 v[156:157], s[8:9], 0, v[138:139]
	s_add_i32 m0, s56, 0x2000
	s_nop 0
	global_load_lds_dwordx4 v[156:157], off
	v_lshl_add_u64 v[156:157], v[212:213], 0, s[38:39]
	s_mov_b32 m0, s84
	s_nop 0
	global_load_lds_dwordx4 v[156:157], off
	v_lshl_add_u64 v[156:157], v[214:215], 0, s[38:39]
	s_mov_b32 m0, s85
	s_nop 0
	global_load_lds_dwordx4 v[156:157], off
	s_waitcnt vmcnt(8)
	s_waitcnt lgkmcnt(0)
	s_barrier
	s_setprio 1
	s_waitcnt lgkmcnt(0)
	v_mfma_f32_16x16x32_bf16 v[62:65], v[130:133], v[178:181], v[62:65]
	v_mfma_f32_16x16x32_bf16 v[58:61], v[148:151], v[178:181], v[58:61]
	v_mfma_f32_16x16x32_bf16 v[46:49], v[130:133], v[186:189], v[46:49]
	v_mfma_f32_16x16x32_bf16 v[42:45], v[148:151], v[186:189], v[42:45]
	v_mfma_f32_16x16x32_bf16 v[28:31], v[130:133], v[194:197], v[28:31]
	v_mfma_f32_16x16x32_bf16 v[24:27], v[148:151], v[194:197], v[24:27]
	v_mfma_f32_16x16x32_bf16 v[12:15], v[130:133], v[202:205], v[12:15]
	v_mfma_f32_16x16x32_bf16 v[8:11], v[148:151], v[202:205], v[8:11]
	v_mfma_f32_16x16x32_bf16 v[62:65], v[134:137], v[182:185], v[62:65]
	v_mfma_f32_16x16x32_bf16 v[58:61], v[152:155], v[182:185], v[58:61]
	v_mfma_f32_16x16x32_bf16 v[46:49], v[134:137], v[190:193], v[46:49]
	v_mfma_f32_16x16x32_bf16 v[42:45], v[152:155], v[190:193], v[42:45]
	v_mfma_f32_16x16x32_bf16 v[28:31], v[134:137], v[198:201], v[28:31]
	v_mfma_f32_16x16x32_bf16 v[24:27], v[152:155], v[198:201], v[24:27]
	v_mfma_f32_16x16x32_bf16 v[12:15], v[134:137], v[206:209], v[12:15]
	v_mfma_f32_16x16x32_bf16 v[8:11], v[152:155], v[206:209], v[8:11]
	v_mfma_f32_16x16x32_bf16 v[54:57], v[162:165], v[178:181], v[54:57]
	v_mfma_f32_16x16x32_bf16 v[50:53], v[170:173], v[178:181], v[50:53]
	v_mfma_f32_16x16x32_bf16 v[38:41], v[162:165], v[186:189], v[38:41]
	v_mfma_f32_16x16x32_bf16 v[34:37], v[170:173], v[186:189], v[34:37]
	v_mfma_f32_16x16x32_bf16 v[20:23], v[162:165], v[194:197], v[20:23]
	v_mfma_f32_16x16x32_bf16 v[16:19], v[170:173], v[194:197], v[16:19]
	v_mfma_f32_16x16x32_bf16 v[4:7], v[162:165], v[202:205], v[4:7]
	v_mfma_f32_16x16x32_bf16 v[0:3], v[170:173], v[202:205], v[0:3]
	v_mfma_f32_16x16x32_bf16 v[54:57], v[166:169], v[182:185], v[54:57]
	v_mfma_f32_16x16x32_bf16 v[50:53], v[174:177], v[182:185], v[50:53]
	v_mfma_f32_16x16x32_bf16 v[38:41], v[166:169], v[190:193], v[38:41]
	v_mfma_f32_16x16x32_bf16 v[34:37], v[174:177], v[190:193], v[34:37]
	v_mfma_f32_16x16x32_bf16 v[20:23], v[166:169], v[198:201], v[20:23]
	v_mfma_f32_16x16x32_bf16 v[16:19], v[174:177], v[198:201], v[16:19]
	v_mfma_f32_16x16x32_bf16 v[4:7], v[166:169], v[206:209], v[4:7]
	v_mfma_f32_16x16x32_bf16 v[0:3], v[174:177], v[206:209], v[0:3]
	s_setprio 0
	s_barrier
	s_add_i32 s93, s93, 2
	s_add_u32 s10, s10, 0x100
	s_addc_u32 s11, s11, 0
	s_add_u32 s91, s91, 0x100
	s_addc_u32 s92, s92, 0
	s_cmp_gt_u32 s93, 13
	s_cbranch_scc0 .LBB0_652
	s_and_b64 vcc, exec, s[16:17]
	s_cbranch_vccz .LBB0_655
	s_barrier

.LBB0_1534:
	s_add_u32 s14, s72, 0x100
	s_addc_u32 s15, s73, 0
	s_add_i32 s9, 0, 0x10000
	s_cmp_eq_u32 s8, 4
	s_cselect_b32 s77, s45, s15
	s_cselect_b32 s76, s44, s14
	s_cselect_b32 s75, s35, s97
	s_cselect_b32 s74, vcc_lo, s96
	s_add_i32 s56, 0, 0x14000
	v_add_u32_e32 v142, s9, v205
	v_add_u32_e32 v158, s56, v205
	ds_read_b128 v[130:133], v142
	ds_read_b128 v[134:137], v142 offset:1024
	ds_read_b128 v[138:141], v142 offset:2048
	ds_read_b128 v[142:145], v142 offset:3072
	ds_read_b128 v[146:149], v158
	ds_read_b128 v[150:153], v158 offset:1024
	ds_read_b128 v[154:157], v158 offset:2048
	ds_read_b128 v[158:161], v158 offset:3072
	v_lshl_add_u64 v[208:209], s[72:73], 0, v[172:173]
	s_add_i32 m0, s85, 0xc000
	ds_read_b128 v[162:165], v207
	ds_read_b128 v[176:179], v207 offset:1024
	ds_read_b128 v[180:183], v207 offset:2048
	ds_read_b128 v[184:187], v207 offset:3072
	ds_read_b128 v[188:191], v207 offset:4096
	ds_read_b128 v[192:195], v207 offset:5120
	ds_read_b128 v[196:199], v207 offset:6144
	ds_read_b128 v[200:203], v207 offset:7168
	global_load_lds_dwordx4 v[208:209], off
	v_lshl_add_u64 v[208:209], s[72:73], 0, v[174:175]
	s_add_i32 m0, s85, 0xe000
	s_nop 0
	global_load_lds_dwordx4 v[208:209], off
	s_waitcnt vmcnt(8)
	s_waitcnt lgkmcnt(0)
	s_barrier
	s_setprio 1
	s_waitcnt lgkmcnt(0)
	v_mfma_f32_16x16x32_bf16 v[126:129], v[130:133], v[162:165], v[126:129]
	v_mfma_f32_16x16x32_bf16 v[122:125], v[138:141], v[162:165], v[122:125]
	v_mfma_f32_16x16x32_bf16 v[110:113], v[130:133], v[180:183], v[110:113]
	v_mfma_f32_16x16x32_bf16 v[106:109], v[138:141], v[180:183], v[106:109]
	v_mfma_f32_16x16x32_bf16 v[94:97], v[130:133], v[188:191], v[94:97]
	v_mfma_f32_16x16x32_bf16 v[90:93], v[138:141], v[188:191], v[90:93]
	v_mfma_f32_16x16x32_bf16 v[78:81], v[130:133], v[196:199], v[78:81]
	v_mfma_f32_16x16x32_bf16 v[74:77], v[138:141], v[196:199], v[74:77]
	v_mfma_f32_16x16x32_bf16 v[126:129], v[134:137], v[176:179], v[126:129]
	v_mfma_f32_16x16x32_bf16 v[122:125], v[142:145], v[176:179], v[122:125]
	v_mfma_f32_16x16x32_bf16 v[110:113], v[134:137], v[184:187], v[110:113]
	v_mfma_f32_16x16x32_bf16 v[106:109], v[142:145], v[184:187], v[106:109]
	v_mfma_f32_16x16x32_bf16 v[94:97], v[134:137], v[192:195], v[94:97]
	v_mfma_f32_16x16x32_bf16 v[90:93], v[142:145], v[192:195], v[90:93]
	v_mfma_f32_16x16x32_bf16 v[78:81], v[134:137], v[200:203], v[78:81]
	v_mfma_f32_16x16x32_bf16 v[74:77], v[142:145], v[200:203], v[74:77]
	v_mfma_f32_16x16x32_bf16 v[118:121], v[146:149], v[162:165], v[118:121]
	v_mfma_f32_16x16x32_bf16 v[114:117], v[154:157], v[162:165], v[114:117]
	v_mfma_f32_16x16x32_bf16 v[102:105], v[146:149], v[180:183], v[102:105]
	v_mfma_f32_16x16x32_bf16 v[98:101], v[154:157], v[180:183], v[98:101]
	v_mfma_f32_16x16x32_bf16 v[86:89], v[146:149], v[188:191], v[86:89]
	v_mfma_f32_16x16x32_bf16 v[82:85], v[154:157], v[188:191], v[82:85]
	v_mfma_f32_16x16x32_bf16 v[70:73], v[146:149], v[196:199], v[70:73]
	v_mfma_f32_16x16x32_bf16 v[66:69], v[154:157], v[196:199], v[66:69]
	v_mfma_f32_16x16x32_bf16 v[118:121], v[150:153], v[176:179], v[118:121]
	v_mfma_f32_16x16x32_bf16 v[114:117], v[158:161], v[176:179], v[114:117]
	v_mfma_f32_16x16x32_bf16 v[102:105], v[150:153], v[184:187], v[102:105]
	v_mfma_f32_16x16x32_bf16 v[98:101], v[158:161], v[184:187], v[98:101]
	v_mfma_f32_16x16x32_bf16 v[86:89], v[150:153], v[192:195], v[86:89]
	v_mfma_f32_16x16x32_bf16 v[82:85], v[158:161], v[192:195], v[82:85]
	v_mfma_f32_16x16x32_bf16 v[70:73], v[150:153], v[200:203], v[70:73]
	v_mfma_f32_16x16x32_bf16 v[66:69], v[158:161], v[200:203], v[66:69]
	s_setprio 0
	s_barrier
	s_add_i32 s9, s9, s84
	v_lshl_add_u64 v[208:209], s[74:75], 0, v[32:33]
	s_mov_b32 m0, s9
	ds_read_b128 v[162:165], v207 offset:16384
	ds_read_b128 v[176:179], v207 offset:17408
	ds_read_b128 v[180:183], v207 offset:18432
	ds_read_b128 v[184:187], v207 offset:19456
	ds_read_b128 v[188:191], v207 offset:20480
	ds_read_b128 v[192:195], v207 offset:21504
	ds_read_b128 v[196:199], v207 offset:22528
	ds_read_b128 v[200:203], v207 offset:23552
	global_load_lds_dwordx4 v[208:209], off
	s_add_i32 m0, s9, 0x2000
	s_add_u32 s72, s74, 0x20000
	v_lshl_add_u64 v[210:211], s[74:75], 0, v[166:167]
	s_addc_u32 s73, s75, 0
	s_add_i32 s9, s56, s84
	global_load_lds_dwordx4 v[210:211], off
	v_lshl_add_u64 v[212:213], s[72:73], 0, v[32:33]
	s_mov_b32 m0, s9
	v_lshl_add_u64 v[214:215], s[76:77], 0, v[168:169]
	global_load_lds_dwordx4 v[212:213], off
	v_lshl_add_u64 v[212:213], s[72:73], 0, v[166:167]
	s_add_i32 m0, s9, 0x2000
	s_nop 0
	global_load_lds_dwordx4 v[212:213], off
	v_lshl_add_u64 v[212:213], s[76:77], 0, v[170:171]
	s_mov_b32 m0, s85
	s_nop 0
	global_load_lds_dwordx4 v[212:213], off
	s_mov_b32 m0, s86
	s_nop 0
	global_load_lds_dwordx4 v[214:215], off
	s_waitcnt vmcnt(8)
	s_waitcnt lgkmcnt(0)
	s_barrier
	s_setprio 1
	s_waitcnt lgkmcnt(0)
	v_mfma_f32_16x16x32_bf16 v[62:65], v[130:133], v[162:165], v[62:65]
	v_mfma_f32_16x16x32_bf16 v[58:61], v[138:141], v[162:165], v[58:61]
	v_mfma_f32_16x16x32_bf16 v[46:49], v[130:133], v[180:183], v[46:49]
	v_mfma_f32_16x16x32_bf16 v[42:45], v[138:141], v[180:183], v[42:45]
	v_mfma_f32_16x16x32_bf16 v[28:31], v[130:133], v[188:191], v[28:31]
	v_mfma_f32_16x16x32_bf16 v[24:27], v[138:141], v[188:191], v[24:27]
	v_mfma_f32_16x16x32_bf16 v[12:15], v[130:133], v[196:199], v[12:15]
	v_mfma_f32_16x16x32_bf16 v[8:11], v[138:141], v[196:199], v[8:11]
	v_mfma_f32_16x16x32_bf16 v[62:65], v[134:137], v[176:179], v[62:65]
	v_mfma_f32_16x16x32_bf16 v[58:61], v[142:145], v[176:179], v[58:61]
	v_mfma_f32_16x16x32_bf16 v[46:49], v[134:137], v[184:187], v[46:49]
	v_mfma_f32_16x16x32_bf16 v[42:45], v[142:145], v[184:187], v[42:45]
	v_mfma_f32_16x16x32_bf16 v[28:31], v[134:137], v[192:195], v[28:31]
	v_mfma_f32_16x16x32_bf16 v[24:27], v[142:145], v[192:195], v[24:27]
	v_mfma_f32_16x16x32_bf16 v[12:15], v[134:137], v[200:203], v[12:15]
	v_mfma_f32_16x16x32_bf16 v[8:11], v[142:145], v[200:203], v[8:11]
	v_mfma_f32_16x16x32_bf16 v[54:57], v[146:149], v[162:165], v[54:57]
	v_mfma_f32_16x16x32_bf16 v[50:53], v[154:157], v[162:165], v[50:53]
	v_mfma_f32_16x16x32_bf16 v[38:41], v[146:149], v[180:183], v[38:41]
	v_mfma_f32_16x16x32_bf16 v[34:37], v[154:157], v[180:183], v[34:37]
	v_mfma_f32_16x16x32_bf16 v[20:23], v[146:149], v[188:191], v[20:23]
	v_mfma_f32_16x16x32_bf16 v[16:19], v[154:157], v[188:191], v[16:19]
	v_mfma_f32_16x16x32_bf16 v[4:7], v[146:149], v[196:199], v[4:7]
	v_mfma_f32_16x16x32_bf16 v[0:3], v[154:157], v[196:199], v[0:3]
	v_mfma_f32_16x16x32_bf16 v[54:57], v[150:153], v[176:179], v[54:57]
	v_mfma_f32_16x16x32_bf16 v[50:53], v[158:161], v[176:179], v[50:53]
	v_mfma_f32_16x16x32_bf16 v[38:41], v[150:153], v[184:187], v[38:41]
	v_mfma_f32_16x16x32_bf16 v[34:37], v[158:161], v[184:187], v[34:37]
	v_mfma_f32_16x16x32_bf16 v[20:23], v[150:153], v[192:195], v[20:23]
	v_mfma_f32_16x16x32_bf16 v[16:19], v[158:161], v[192:195], v[16:19]
	v_mfma_f32_16x16x32_bf16 v[4:7], v[150:153], v[200:203], v[4:7]
	v_mfma_f32_16x16x32_bf16 v[0:3], v[158:161], v[200:203], v[0:3]
	s_setprio 0
	s_barrier
	s_add_i32 s9, 0, 0x18000
	s_add_i32 s56, 0, 0x1c000
	v_add_u32_e32 v142, s9, v205
	v_add_u32_e32 v158, s56, v205
	ds_read_b128 v[130:133], v142
	ds_read_b128 v[134:137], v142 offset:1024
	ds_read_b128 v[138:141], v142 offset:2048
	ds_read_b128 v[142:145], v142 offset:3072
	ds_read_b128 v[146:149], v158
	ds_read_b128 v[150:153], v158 offset:1024
	ds_read_b128 v[154:157], v158 offset:2048
	ds_read_b128 v[158:161], v158 offset:3072
	s_add_u32 s72, s76, 0x2a0000
	s_addc_u32 s73, s77, 0
	s_mov_b32 m0, s87
	v_lshl_add_u64 v[216:217], s[72:73], 0, v[170:171]
	ds_read_b128 v[162:165], v207 offset:32768
	ds_read_b128 v[176:179], v207 offset:33792
	ds_read_b128 v[180:183], v207 offset:34816
	ds_read_b128 v[184:187], v207 offset:35840
	ds_read_b128 v[188:191], v207 offset:36864
	ds_read_b128 v[192:195], v207 offset:37888
	ds_read_b128 v[196:199], v207 offset:38912
	ds_read_b128 v[200:203], v207 offset:39936
	global_load_lds_dwordx4 v[216:217], off
	v_lshl_add_u64 v[216:217], s[72:73], 0, v[168:169]
	s_mov_b32 m0, s88
	s_nop 0
	global_load_lds_dwordx4 v[216:217], off
	s_waitcnt vmcnt(8)
	s_waitcnt lgkmcnt(0)
	s_barrier
	s_setprio 1
	s_waitcnt lgkmcnt(0)
	v_mfma_f32_16x16x32_bf16 v[126:129], v[130:133], v[162:165], v[126:129]
	v_mfma_f32_16x16x32_bf16 v[122:125], v[138:141], v[162:165], v[122:125]
	v_mfma_f32_16x16x32_bf16 v[110:113], v[130:133], v[180:183], v[110:113]
	v_mfma_f32_16x16x32_bf16 v[106:109], v[138:141], v[180:183], v[106:109]
	v_mfma_f32_16x16x32_bf16 v[94:97], v[130:133], v[188:191], v[94:97]
	v_mfma_f32_16x16x32_bf16 v[90:93], v[138:141], v[188:191], v[90:93]
	v_mfma_f32_16x16x32_bf16 v[78:81], v[130:133], v[196:199], v[78:81]
	v_mfma_f32_16x16x32_bf16 v[74:77], v[138:141], v[196:199], v[74:77]
	v_mfma_f32_16x16x32_bf16 v[126:129], v[134:137], v[176:179], v[126:129]
	v_mfma_f32_16x16x32_bf16 v[122:125], v[142:145], v[176:179], v[122:125]
	v_mfma_f32_16x16x32_bf16 v[110:113], v[134:137], v[184:187], v[110:113]
	v_mfma_f32_16x16x32_bf16 v[106:109], v[142:145], v[184:187], v[106:109]
	v_mfma_f32_16x16x32_bf16 v[94:97], v[134:137], v[192:195], v[94:97]
	v_mfma_f32_16x16x32_bf16 v[90:93], v[142:145], v[192:195], v[90:93]
	v_mfma_f32_16x16x32_bf16 v[78:81], v[134:137], v[200:203], v[78:81]
	v_mfma_f32_16x16x32_bf16 v[74:77], v[142:145], v[200:203], v[74:77]
	v_mfma_f32_16x16x32_bf16 v[118:121], v[146:149], v[162:165], v[118:121]
	v_mfma_f32_16x16x32_bf16 v[114:117], v[154:157], v[162:165], v[114:117]
	v_mfma_f32_16x16x32_bf16 v[102:105], v[146:149], v[180:183], v[102:105]
	v_mfma_f32_16x16x32_bf16 v[98:101], v[154:157], v[180:183], v[98:101]
	v_mfma_f32_16x16x32_bf16 v[86:89], v[146:149], v[188:191], v[86:89]
	v_mfma_f32_16x16x32_bf16 v[82:85], v[154:157], v[188:191], v[82:85]
	v_mfma_f32_16x16x32_bf16 v[70:73], v[146:149], v[196:199], v[70:73]
	v_mfma_f32_16x16x32_bf16 v[66:69], v[154:157], v[196:199], v[66:69]
	v_mfma_f32_16x16x32_bf16 v[118:121], v[150:153], v[176:179], v[118:121]
	v_mfma_f32_16x16x32_bf16 v[114:117], v[158:161], v[176:179], v[114:117]
	v_mfma_f32_16x16x32_bf16 v[102:105], v[150:153], v[184:187], v[102:105]
	v_mfma_f32_16x16x32_bf16 v[98:101], v[158:161], v[184:187], v[98:101]
	v_mfma_f32_16x16x32_bf16 v[86:89], v[150:153], v[192:195], v[86:89]
	v_mfma_f32_16x16x32_bf16 v[82:85], v[158:161], v[192:195], v[82:85]
	v_mfma_f32_16x16x32_bf16 v[70:73], v[150:153], v[200:203], v[70:73]
	v_mfma_f32_16x16x32_bf16 v[66:69], v[158:161], v[200:203], v[66:69]
	s_setprio 0
	s_barrier
	s_add_i32 s9, s9, s84
	v_lshl_add_u64 v[208:209], v[208:209], 0, s[38:39]
	s_mov_b32 m0, s9
	ds_read_b128 v[162:165], v207 offset:49152
	ds_read_b128 v[176:179], v207 offset:50176
	ds_read_b128 v[180:183], v207 offset:51200
	ds_read_b128 v[184:187], v207 offset:52224
	ds_read_b128 v[188:191], v207 offset:53248
	ds_read_b128 v[192:195], v207 offset:54272
	ds_read_b128 v[196:199], v207 offset:55296
	ds_read_b128 v[200:203], v207 offset:56320
	global_load_lds_dwordx4 v[208:209], off
	s_add_i32 m0, s9, 0x2000
	s_add_u32 s72, s74, 0x20080
	v_lshl_add_u64 v[208:209], v[210:211], 0, s[38:39]
	s_addc_u32 s73, s75, 0
	s_add_i32 s9, s56, s84
	global_load_lds_dwordx4 v[208:209], off
	v_lshl_add_u64 v[208:209], s[72:73], 0, v[32:33]
	s_mov_b32 m0, s9
	s_nop 0
	global_load_lds_dwordx4 v[208:209], off
	v_lshl_add_u64 v[208:209], s[72:73], 0, v[166:167]
	s_add_i32 m0, s9, 0x2000
	s_nop 0
	global_load_lds_dwordx4 v[208:209], off
	v_lshl_add_u64 v[208:209], v[212:213], 0, s[38:39]
	s_mov_b32 m0, s89
	s_nop 0
	global_load_lds_dwordx4 v[208:209], off
	v_lshl_add_u64 v[208:209], v[214:215], 0, s[38:39]
	s_mov_b32 m0, s90
	s_nop 0
	global_load_lds_dwordx4 v[208:209], off
	s_waitcnt vmcnt(8)
	s_waitcnt lgkmcnt(0)
	s_barrier
	s_setprio 1
	s_waitcnt lgkmcnt(0)
	v_mfma_f32_16x16x32_bf16 v[62:65], v[130:133], v[162:165], v[62:65]
	v_mfma_f32_16x16x32_bf16 v[58:61], v[138:141], v[162:165], v[58:61]
	v_mfma_f32_16x16x32_bf16 v[46:49], v[130:133], v[180:183], v[46:49]
	v_mfma_f32_16x16x32_bf16 v[42:45], v[138:141], v[180:183], v[42:45]
	v_mfma_f32_16x16x32_bf16 v[28:31], v[130:133], v[188:191], v[28:31]
	v_mfma_f32_16x16x32_bf16 v[24:27], v[138:141], v[188:191], v[24:27]
	v_mfma_f32_16x16x32_bf16 v[12:15], v[130:133], v[196:199], v[12:15]
	v_mfma_f32_16x16x32_bf16 v[8:11], v[138:141], v[196:199], v[8:11]
	v_mfma_f32_16x16x32_bf16 v[62:65], v[134:137], v[176:179], v[62:65]
	v_mfma_f32_16x16x32_bf16 v[58:61], v[142:145], v[176:179], v[58:61]
	v_mfma_f32_16x16x32_bf16 v[46:49], v[134:137], v[184:187], v[46:49]
	v_mfma_f32_16x16x32_bf16 v[42:45], v[142:145], v[184:187], v[42:45]
	v_mfma_f32_16x16x32_bf16 v[28:31], v[134:137], v[192:195], v[28:31]
	v_mfma_f32_16x16x32_bf16 v[24:27], v[142:145], v[192:195], v[24:27]
	v_mfma_f32_16x16x32_bf16 v[12:15], v[134:137], v[200:203], v[12:15]
	v_mfma_f32_16x16x32_bf16 v[8:11], v[142:145], v[200:203], v[8:11]
	v_mfma_f32_16x16x32_bf16 v[54:57], v[146:149], v[162:165], v[54:57]
	v_mfma_f32_16x16x32_bf16 v[50:53], v[154:157], v[162:165], v[50:53]
	v_mfma_f32_16x16x32_bf16 v[38:41], v[146:149], v[180:183], v[38:41]
	v_mfma_f32_16x16x32_bf16 v[34:37], v[154:157], v[180:183], v[34:37]
	v_mfma_f32_16x16x32_bf16 v[20:23], v[146:149], v[188:191], v[20:23]
	v_mfma_f32_16x16x32_bf16 v[16:19], v[154:157], v[188:191], v[16:19]
	v_mfma_f32_16x16x32_bf16 v[4:7], v[146:149], v[196:199], v[4:7]
	v_mfma_f32_16x16x32_bf16 v[0:3], v[154:157], v[196:199], v[0:3]
	v_mfma_f32_16x16x32_bf16 v[54:57], v[150:153], v[176:179], v[54:57]
	v_mfma_f32_16x16x32_bf16 v[50:53], v[158:161], v[176:179], v[50:53]
	v_mfma_f32_16x16x32_bf16 v[38:41], v[150:153], v[184:187], v[38:41]
	v_mfma_f32_16x16x32_bf16 v[34:37], v[158:161], v[184:187], v[34:37]
	v_mfma_f32_16x16x32_bf16 v[20:23], v[150:153], v[192:195], v[20:23]
	v_mfma_f32_16x16x32_bf16 v[16:19], v[158:161], v[192:195], v[16:19]
	v_mfma_f32_16x16x32_bf16 v[4:7], v[150:153], v[200:203], v[4:7]
	v_mfma_f32_16x16x32_bf16 v[0:3], v[158:161], v[200:203], v[0:3]
	s_setprio 0
	s_barrier
	s_add_i32 s8, s8, 2
	s_add_u32 s96, s96, 0x100
	s_addc_u32 s97, s97, 0
	s_cmp_gt_u32 s8, 5
	s_mov_b64 s[72:73], s[14:15]
	s_cbranch_scc0 .LBB0_1534
	s_and_b64 vcc, exec, s[18:19]
	s_cbranch_vccz .LBB0_1537
	s_barrier

.LBB0_1640:
	s_add_u32 s9, s14, 0xfffc0080
	s_addc_u32 s56, s15, -1
	s_add_i32 s57, 0, 0x10000
	s_cmp_eq_u32 s8, 12
	s_cselect_b32 vcc_hi, s67, s56
	s_cselect_b32 vcc_lo, s94, s9
	s_cselect_b32 s75, s45, s97
	s_cselect_b32 s74, s95, s96
	s_add_i32 s9, 0, 0x14000
	v_add_u32_e32 v142, s57, v228
	v_add_u32_e32 v158, s9, v228
	ds_read_b128 v[122:125], v142
	ds_read_b128 v[134:137], v142 offset:1024
	ds_read_b128 v[138:141], v142 offset:2048
	ds_read_b128 v[142:145], v142 offset:3072
	ds_read_b128 v[146:149], v158
	ds_read_b128 v[150:153], v158 offset:1024
	ds_read_b128 v[154:157], v158 offset:2048
	ds_read_b128 v[158:161], v158 offset:3072
	v_lshl_add_u64 v[194:195], s[14:15], 0, v[202:203]
	s_add_i32 m0, s86, 0xc000
	ds_read_b128 v[162:165], v230
	ds_read_b128 v[166:169], v230 offset:1024
	ds_read_b128 v[170:173], v230 offset:2048
	ds_read_b128 v[174:177], v230 offset:3072
	ds_read_b128 v[178:181], v230 offset:4096
	ds_read_b128 v[182:185], v230 offset:5120
	ds_read_b128 v[186:189], v230 offset:6144
	ds_read_b128 v[190:193], v230 offset:7168
	global_load_lds_dwordx4 v[194:195], off
	v_lshl_add_u64 v[194:195], s[14:15], 0, v[204:205]
	s_add_i32 m0, s86, 0xe000
	s_nop 0
	global_load_lds_dwordx4 v[194:195], off
	s_waitcnt vmcnt(8)
	s_waitcnt lgkmcnt(0)
	s_barrier
	s_setprio 1
	s_waitcnt lgkmcnt(0)
	v_mfma_f32_16x16x32_bf16 v[130:133], v[122:125], v[162:165], v[130:133]
	v_mfma_f32_16x16x32_bf16 v[126:129], v[138:141], v[162:165], v[126:129]
	v_mfma_f32_16x16x32_bf16 v[110:113], v[122:125], v[170:173], v[110:113]
	v_mfma_f32_16x16x32_bf16 v[106:109], v[138:141], v[170:173], v[106:109]
	v_mfma_f32_16x16x32_bf16 v[94:97], v[122:125], v[178:181], v[94:97]
	v_mfma_f32_16x16x32_bf16 v[90:93], v[138:141], v[178:181], v[90:93]
	v_mfma_f32_16x16x32_bf16 v[78:81], v[122:125], v[186:189], v[78:81]
	v_mfma_f32_16x16x32_bf16 v[74:77], v[138:141], v[186:189], v[74:77]
	v_mfma_f32_16x16x32_bf16 v[130:133], v[134:137], v[166:169], v[130:133]
	v_mfma_f32_16x16x32_bf16 v[126:129], v[142:145], v[166:169], v[126:129]
	v_mfma_f32_16x16x32_bf16 v[110:113], v[134:137], v[174:177], v[110:113]
	v_mfma_f32_16x16x32_bf16 v[106:109], v[142:145], v[174:177], v[106:109]
	v_mfma_f32_16x16x32_bf16 v[94:97], v[134:137], v[182:185], v[94:97]
	v_mfma_f32_16x16x32_bf16 v[90:93], v[142:145], v[182:185], v[90:93]
	v_mfma_f32_16x16x32_bf16 v[78:81], v[134:137], v[190:193], v[78:81]
	v_mfma_f32_16x16x32_bf16 v[74:77], v[142:145], v[190:193], v[74:77]
	v_mfma_f32_16x16x32_bf16 v[118:121], v[146:149], v[162:165], v[118:121]
	v_mfma_f32_16x16x32_bf16 v[114:117], v[154:157], v[162:165], v[114:117]
	v_mfma_f32_16x16x32_bf16 v[102:105], v[146:149], v[170:173], v[102:105]
	v_mfma_f32_16x16x32_bf16 v[98:101], v[154:157], v[170:173], v[98:101]
	v_mfma_f32_16x16x32_bf16 v[86:89], v[146:149], v[178:181], v[86:89]
	v_mfma_f32_16x16x32_bf16 v[82:85], v[154:157], v[178:181], v[82:85]
	v_mfma_f32_16x16x32_bf16 v[70:73], v[146:149], v[186:189], v[70:73]
	v_mfma_f32_16x16x32_bf16 v[66:69], v[154:157], v[186:189], v[66:69]
	v_mfma_f32_16x16x32_bf16 v[118:121], v[150:153], v[166:169], v[118:121]
	v_mfma_f32_16x16x32_bf16 v[114:117], v[158:161], v[166:169], v[114:117]
	v_mfma_f32_16x16x32_bf16 v[102:105], v[150:153], v[174:177], v[102:105]
	v_mfma_f32_16x16x32_bf16 v[98:101], v[158:161], v[174:177], v[98:101]
	v_mfma_f32_16x16x32_bf16 v[86:89], v[150:153], v[182:185], v[86:89]
	v_mfma_f32_16x16x32_bf16 v[82:85], v[158:161], v[182:185], v[82:85]
	v_mfma_f32_16x16x32_bf16 v[70:73], v[150:153], v[190:193], v[70:73]
	v_mfma_f32_16x16x32_bf16 v[66:69], v[158:161], v[190:193], v[66:69]
	s_setprio 0
	s_barrier
	s_add_i32 s56, s57, s85
	v_lshl_add_u64 v[194:195], s[74:75], 0, v[32:33]
	s_mov_b32 m0, s56
	ds_read_b128 v[162:165], v230 offset:16384
	ds_read_b128 v[166:169], v230 offset:17408
	ds_read_b128 v[170:173], v230 offset:18432
	ds_read_b128 v[174:177], v230 offset:19456
	ds_read_b128 v[178:181], v230 offset:20480
	ds_read_b128 v[182:185], v230 offset:21504
	ds_read_b128 v[186:189], v230 offset:22528
	ds_read_b128 v[190:193], v230 offset:23552
	global_load_lds_dwordx4 v[194:195], off
	s_add_i32 m0, s56, 0x2000
	s_add_u32 s56, s74, 0x40000
	v_lshl_add_u64 v[206:207], s[74:75], 0, v[196:197]
	s_addc_u32 s57, s75, 0
	s_add_i32 s9, s9, s85
	global_load_lds_dwordx4 v[206:207], off
	v_lshl_add_u64 v[208:209], s[56:57], 0, v[32:33]
	s_mov_b32 m0, s9
	v_lshl_add_u64 v[210:211], vcc, 0, v[198:199]
	global_load_lds_dwordx4 v[208:209], off
	v_lshl_add_u64 v[208:209], s[56:57], 0, v[196:197]
	s_add_i32 m0, s9, 0x2000
	s_nop 0
	global_load_lds_dwordx4 v[208:209], off
	v_lshl_add_u64 v[208:209], vcc, 0, v[200:201]
	s_mov_b32 m0, s86
	s_nop 0
	global_load_lds_dwordx4 v[208:209], off
	s_mov_b32 m0, s87
	s_nop 0
	global_load_lds_dwordx4 v[210:211], off
	s_waitcnt vmcnt(8)
	s_waitcnt lgkmcnt(0)
	s_barrier
	s_setprio 1
	s_waitcnt lgkmcnt(0)
	v_mfma_f32_16x16x32_bf16 v[62:65], v[122:125], v[162:165], v[62:65]
	v_mfma_f32_16x16x32_bf16 v[58:61], v[138:141], v[162:165], v[58:61]
	v_mfma_f32_16x16x32_bf16 v[46:49], v[122:125], v[170:173], v[46:49]
	v_mfma_f32_16x16x32_bf16 v[42:45], v[138:141], v[170:173], v[42:45]
	v_mfma_f32_16x16x32_bf16 v[28:31], v[122:125], v[178:181], v[28:31]
	v_mfma_f32_16x16x32_bf16 v[24:27], v[138:141], v[178:181], v[24:27]
	v_mfma_f32_16x16x32_bf16 v[12:15], v[122:125], v[186:189], v[12:15]
	v_mfma_f32_16x16x32_bf16 v[8:11], v[138:141], v[186:189], v[8:11]
	v_mfma_f32_16x16x32_bf16 v[62:65], v[134:137], v[166:169], v[62:65]
	v_mfma_f32_16x16x32_bf16 v[58:61], v[142:145], v[166:169], v[58:61]
	v_mfma_f32_16x16x32_bf16 v[46:49], v[134:137], v[174:177], v[46:49]
	v_mfma_f32_16x16x32_bf16 v[42:45], v[142:145], v[174:177], v[42:45]
	v_mfma_f32_16x16x32_bf16 v[28:31], v[134:137], v[182:185], v[28:31]
	v_mfma_f32_16x16x32_bf16 v[24:27], v[142:145], v[182:185], v[24:27]
	v_mfma_f32_16x16x32_bf16 v[12:15], v[134:137], v[190:193], v[12:15]
	v_mfma_f32_16x16x32_bf16 v[8:11], v[142:145], v[190:193], v[8:11]
	v_mfma_f32_16x16x32_bf16 v[54:57], v[146:149], v[162:165], v[54:57]
	v_mfma_f32_16x16x32_bf16 v[50:53], v[154:157], v[162:165], v[50:53]
	v_mfma_f32_16x16x32_bf16 v[38:41], v[146:149], v[170:173], v[38:41]
	v_mfma_f32_16x16x32_bf16 v[34:37], v[154:157], v[170:173], v[34:37]
	v_mfma_f32_16x16x32_bf16 v[20:23], v[146:149], v[178:181], v[20:23]
	v_mfma_f32_16x16x32_bf16 v[16:19], v[154:157], v[178:181], v[16:19]
	v_mfma_f32_16x16x32_bf16 v[4:7], v[146:149], v[186:189], v[4:7]
	v_mfma_f32_16x16x32_bf16 v[0:3], v[154:157], v[186:189], v[0:3]
	v_mfma_f32_16x16x32_bf16 v[54:57], v[150:153], v[166:169], v[54:57]
	v_mfma_f32_16x16x32_bf16 v[50:53], v[158:161], v[166:169], v[50:53]
	v_mfma_f32_16x16x32_bf16 v[38:41], v[150:153], v[174:177], v[38:41]
	v_mfma_f32_16x16x32_bf16 v[34:37], v[158:161], v[174:177], v[34:37]
	v_mfma_f32_16x16x32_bf16 v[20:23], v[150:153], v[182:185], v[20:23]
	v_mfma_f32_16x16x32_bf16 v[16:19], v[158:161], v[182:185], v[16:19]
	v_mfma_f32_16x16x32_bf16 v[4:7], v[150:153], v[190:193], v[4:7]
	v_mfma_f32_16x16x32_bf16 v[0:3], v[158:161], v[190:193], v[0:3]
	s_setprio 0
	s_barrier
	s_add_i32 s9, 0, 0x18000
	s_add_i32 s64, 0, 0x1c000
	v_add_u32_e32 v142, s9, v228
	v_add_u32_e32 v158, s64, v228
	ds_read_b128 v[122:125], v142
	ds_read_b128 v[134:137], v142 offset:1024
	ds_read_b128 v[138:141], v142 offset:2048
	ds_read_b128 v[142:145], v142 offset:3072
	ds_read_b128 v[146:149], v158
	ds_read_b128 v[150:153], v158 offset:1024
	ds_read_b128 v[154:157], v158 offset:2048
	ds_read_b128 v[158:161], v158 offset:3072
	s_add_u32 s56, vcc_lo, 0x40000
	s_addc_u32 s57, vcc_hi, 0
	s_mov_b32 m0, s88
	v_lshl_add_u64 v[212:213], s[56:57], 0, v[200:201]
	ds_read_b128 v[162:165], v230 offset:32768
	ds_read_b128 v[166:169], v230 offset:33792
	ds_read_b128 v[170:173], v230 offset:34816
	ds_read_b128 v[174:177], v230 offset:35840
	ds_read_b128 v[178:181], v230 offset:36864
	ds_read_b128 v[182:185], v230 offset:37888
	ds_read_b128 v[186:189], v230 offset:38912
	ds_read_b128 v[190:193], v230 offset:39936
	global_load_lds_dwordx4 v[212:213], off
	v_lshl_add_u64 v[212:213], s[56:57], 0, v[198:199]
	s_mov_b32 m0, s89
	s_nop 0
	global_load_lds_dwordx4 v[212:213], off
	s_waitcnt vmcnt(8)
	s_waitcnt lgkmcnt(0)
	s_barrier
	s_setprio 1
	s_waitcnt lgkmcnt(0)
	v_mfma_f32_16x16x32_bf16 v[130:133], v[122:125], v[162:165], v[130:133]
	v_mfma_f32_16x16x32_bf16 v[126:129], v[138:141], v[162:165], v[126:129]
	v_mfma_f32_16x16x32_bf16 v[110:113], v[122:125], v[170:173], v[110:113]
	v_mfma_f32_16x16x32_bf16 v[106:109], v[138:141], v[170:173], v[106:109]
	v_mfma_f32_16x16x32_bf16 v[94:97], v[122:125], v[178:181], v[94:97]
	v_mfma_f32_16x16x32_bf16 v[90:93], v[138:141], v[178:181], v[90:93]
	v_mfma_f32_16x16x32_bf16 v[78:81], v[122:125], v[186:189], v[78:81]
	v_mfma_f32_16x16x32_bf16 v[74:77], v[138:141], v[186:189], v[74:77]
	v_mfma_f32_16x16x32_bf16 v[130:133], v[134:137], v[166:169], v[130:133]
	v_mfma_f32_16x16x32_bf16 v[126:129], v[142:145], v[166:169], v[126:129]
	v_mfma_f32_16x16x32_bf16 v[110:113], v[134:137], v[174:177], v[110:113]
	v_mfma_f32_16x16x32_bf16 v[106:109], v[142:145], v[174:177], v[106:109]
	v_mfma_f32_16x16x32_bf16 v[94:97], v[134:137], v[182:185], v[94:97]
	v_mfma_f32_16x16x32_bf16 v[90:93], v[142:145], v[182:185], v[90:93]
	v_mfma_f32_16x16x32_bf16 v[78:81], v[134:137], v[190:193], v[78:81]
	v_mfma_f32_16x16x32_bf16 v[74:77], v[142:145], v[190:193], v[74:77]
	v_mfma_f32_16x16x32_bf16 v[118:121], v[146:149], v[162:165], v[118:121]
	v_mfma_f32_16x16x32_bf16 v[114:117], v[154:157], v[162:165], v[114:117]
	v_mfma_f32_16x16x32_bf16 v[102:105], v[146:149], v[170:173], v[102:105]
	v_mfma_f32_16x16x32_bf16 v[98:101], v[154:157], v[170:173], v[98:101]
	v_mfma_f32_16x16x32_bf16 v[86:89], v[146:149], v[178:181], v[86:89]
	v_mfma_f32_16x16x32_bf16 v[82:85], v[154:157], v[178:181], v[82:85]
	v_mfma_f32_16x16x32_bf16 v[70:73], v[146:149], v[186:189], v[70:73]
	v_mfma_f32_16x16x32_bf16 v[66:69], v[154:157], v[186:189], v[66:69]
	v_mfma_f32_16x16x32_bf16 v[118:121], v[150:153], v[166:169], v[118:121]
	v_mfma_f32_16x16x32_bf16 v[114:117], v[158:161], v[166:169], v[114:117]
	v_mfma_f32_16x16x32_bf16 v[102:105], v[150:153], v[174:177], v[102:105]
	v_mfma_f32_16x16x32_bf16 v[98:101], v[158:161], v[174:177], v[98:101]
	v_mfma_f32_16x16x32_bf16 v[86:89], v[150:153], v[182:185], v[86:89]
	v_mfma_f32_16x16x32_bf16 v[82:85], v[158:161], v[182:185], v[82:85]
	v_mfma_f32_16x16x32_bf16 v[70:73], v[150:153], v[190:193], v[70:73]
	v_mfma_f32_16x16x32_bf16 v[66:69], v[158:161], v[190:193], v[66:69]
	s_setprio 0
	s_barrier
	s_add_i32 s9, s9, s85
	v_lshl_add_u64 v[194:195], v[194:195], 0, s[38:39]
	s_mov_b32 m0, s9
	ds_read_b128 v[162:165], v230 offset:49152
	ds_read_b128 v[166:169], v230 offset:50176
	ds_read_b128 v[170:173], v230 offset:51200
	ds_read_b128 v[174:177], v230 offset:52224
	ds_read_b128 v[178:181], v230 offset:53248
	ds_read_b128 v[182:185], v230 offset:54272
	ds_read_b128 v[186:189], v230 offset:55296
	ds_read_b128 v[190:193], v230 offset:56320
	global_load_lds_dwordx4 v[194:195], off
	s_add_i32 m0, s9, 0x2000
	s_add_u32 s56, s74, 0x40080
	v_lshl_add_u64 v[194:195], v[206:207], 0, s[38:39]
	s_addc_u32 s57, s75, 0
	s_add_i32 s9, s64, s85
	global_load_lds_dwordx4 v[194:195], off
	v_lshl_add_u64 v[194:195], s[56:57], 0, v[32:33]
	s_mov_b32 m0, s9
	s_nop 0
	global_load_lds_dwordx4 v[194:195], off
	v_lshl_add_u64 v[194:195], s[56:57], 0, v[196:197]
	s_add_i32 m0, s9, 0x2000
	s_nop 0
	global_load_lds_dwordx4 v[194:195], off
	v_lshl_add_u64 v[194:195], v[208:209], 0, s[38:39]
	s_mov_b32 m0, s28
	s_nop 0
	global_load_lds_dwordx4 v[194:195], off
	v_lshl_add_u64 v[194:195], v[210:211], 0, s[38:39]
	s_mov_b32 m0, s90
	s_nop 0
	global_load_lds_dwordx4 v[194:195], off
	s_waitcnt vmcnt(8)
	s_waitcnt lgkmcnt(0)
	s_barrier
	s_setprio 1
	s_waitcnt lgkmcnt(0)
	v_mfma_f32_16x16x32_bf16 v[62:65], v[122:125], v[162:165], v[62:65]
	v_mfma_f32_16x16x32_bf16 v[58:61], v[138:141], v[162:165], v[58:61]
	v_mfma_f32_16x16x32_bf16 v[46:49], v[122:125], v[170:173], v[46:49]
	v_mfma_f32_16x16x32_bf16 v[42:45], v[138:141], v[170:173], v[42:45]
	v_mfma_f32_16x16x32_bf16 v[28:31], v[122:125], v[178:181], v[28:31]
	v_mfma_f32_16x16x32_bf16 v[24:27], v[138:141], v[178:181], v[24:27]
	v_mfma_f32_16x16x32_bf16 v[12:15], v[122:125], v[186:189], v[12:15]
	v_mfma_f32_16x16x32_bf16 v[8:11], v[138:141], v[186:189], v[8:11]
	v_mfma_f32_16x16x32_bf16 v[62:65], v[134:137], v[166:169], v[62:65]
	v_mfma_f32_16x16x32_bf16 v[58:61], v[142:145], v[166:169], v[58:61]
	v_mfma_f32_16x16x32_bf16 v[46:49], v[134:137], v[174:177], v[46:49]
	v_mfma_f32_16x16x32_bf16 v[42:45], v[142:145], v[174:177], v[42:45]
	v_mfma_f32_16x16x32_bf16 v[28:31], v[134:137], v[182:185], v[28:31]
	v_mfma_f32_16x16x32_bf16 v[24:27], v[142:145], v[182:185], v[24:27]
	v_mfma_f32_16x16x32_bf16 v[12:15], v[134:137], v[190:193], v[12:15]
	v_mfma_f32_16x16x32_bf16 v[8:11], v[142:145], v[190:193], v[8:11]
	v_mfma_f32_16x16x32_bf16 v[54:57], v[146:149], v[162:165], v[54:57]
	v_mfma_f32_16x16x32_bf16 v[50:53], v[154:157], v[162:165], v[50:53]
	v_mfma_f32_16x16x32_bf16 v[38:41], v[146:149], v[170:173], v[38:41]
	v_mfma_f32_16x16x32_bf16 v[34:37], v[154:157], v[170:173], v[34:37]
	v_mfma_f32_16x16x32_bf16 v[20:23], v[146:149], v[178:181], v[20:23]
	v_mfma_f32_16x16x32_bf16 v[16:19], v[154:157], v[178:181], v[16:19]
	v_mfma_f32_16x16x32_bf16 v[4:7], v[146:149], v[186:189], v[4:7]
	v_mfma_f32_16x16x32_bf16 v[0:3], v[154:157], v[186:189], v[0:3]
	v_mfma_f32_16x16x32_bf16 v[54:57], v[150:153], v[166:169], v[54:57]
	v_mfma_f32_16x16x32_bf16 v[50:53], v[158:161], v[166:169], v[50:53]
	v_mfma_f32_16x16x32_bf16 v[38:41], v[150:153], v[174:177], v[38:41]
	v_mfma_f32_16x16x32_bf16 v[34:37], v[158:161], v[174:177], v[34:37]
	v_mfma_f32_16x16x32_bf16 v[20:23], v[150:153], v[182:185], v[20:23]
	v_mfma_f32_16x16x32_bf16 v[16:19], v[158:161], v[182:185], v[16:19]
	v_mfma_f32_16x16x32_bf16 v[4:7], v[150:153], v[190:193], v[4:7]
	v_mfma_f32_16x16x32_bf16 v[0:3], v[158:161], v[190:193], v[0:3]
	s_setprio 0
	s_barrier
	s_add_i32 s8, s8, 2
	s_add_u32 s14, s14, 0x100
	s_addc_u32 s15, s15, 0
	s_add_u32 s96, s96, 0x100
	s_addc_u32 s97, s97, 0
	s_cmp_gt_u32 s8, 13
	s_cbranch_scc0 .LBB0_1640
	s_and_b64 vcc, exec, s[34:35]
	s_cbranch_vccz .LBB0_1643
	s_barrier
